# row-norm wave reductions: last four butterfly steps (xor 8,4,2,1) via DPP adds instead of ds_bpermute round trips in norm0/norm1/final (bit-identical)
# speedup vs baseline: 1.0111x; 1.0111x over previous
.LBB0_99:
	s_or_b64 exec, exec, s[8:9]
	s_waitcnt vmcnt(7)
	v_mov_b32_e32 v50, v37
	s_waitcnt vmcnt(6)
	v_mov_b32_e32 v51, v33
	v_mov_b32_e32 v48, v36
	v_mov_b32_e32 v49, v32
	v_pk_mul_f32 v[50:51], v[50:51], v[50:51]
	s_waitcnt vmcnt(5)
	v_mov_b32_e32 v52, v29
	v_pk_fma_f32 v[48:49], v[48:49], v[48:49], v[50:51]
	v_mov_b32_e32 v50, v38
	v_mov_b32_e32 v51, v34
	v_pk_fma_f32 v[48:49], v[50:51], v[50:51], v[48:49]
	v_mov_b32_e32 v50, v39
	v_mov_b32_e32 v51, v35
	s_waitcnt vmcnt(4)
	v_mov_b32_e32 v53, v25
	v_pk_fma_f32 v[48:49], v[50:51], v[50:51], v[48:49]
	v_mov_b32_e32 v50, v28
	v_mov_b32_e32 v51, v24
	v_pk_mul_f32 v[52:53], v[52:53], v[52:53]
	v_add_f32_e32 v48, v48, v49
	v_pk_fma_f32 v[50:51], v[50:51], v[50:51], v[52:53]
	v_mov_b32_e32 v52, v30
	v_mov_b32_e32 v53, v26
	v_pk_fma_f32 v[50:51], v[52:53], v[52:53], v[50:51]
	v_mov_b32_e32 v52, v31
	v_mov_b32_e32 v53, v27
	v_pk_fma_f32 v[50:51], v[52:53], v[52:53], v[50:51]
	v_ashrrev_i32_e32 v163, 31, v162
	v_add_f32_e32 v48, v48, v50
	v_add_f32_e32 v48, v48, v51
	ds_bpermute_b32 v49, v178, v48
	v_lshlrev_b64 v[52:53], 11, v[162:163]
	v_lshl_add_u64 v[52:53], v[148:149], 0, v[52:53]
	s_waitcnt lgkmcnt(0)
	v_add_f32_e32 v48, v48, v49
	ds_bpermute_b32 v49, v179, v48
	s_waitcnt lgkmcnt(0)
	v_add_f32_e32 v48, v48, v49
	s_nop 1
	v_add_f32_dpp v48, v48, v48 row_ror:8 row_mask:0xf bank_mask:0xf
	s_nop 1
	v_add_f32_dpp v48, v48, v48 row_ror:4 row_mask:0xf bank_mask:0xf
	s_nop 1
	v_add_f32_dpp v50, v48, v48 quad_perm:[2,3,0,1] row_mask:0xf bank_mask:0xf
	v_pk_add_f32 v[48:49], v[22:23], 1.0 op_sel_hi:[1,0]
	s_nop 1
	v_add_f32_dpp v50, v50, v50 quad_perm:[1,0,3,2] row_mask:0xf bank_mask:0xf
	v_fmamk_f32 v50, v50, 0x3a800000, v184
	v_mul_f32_e32 v51, 0x4b800000, v50
	v_cmp_gt_f32_e32 vcc, s14, v50
	s_nop 1
	v_cndmask_b32_e32 v50, v50, v51, vcc
	v_rsq_f32_e32 v54, v50
	v_pk_add_f32 v[50:51], v[20:21], 1.0 op_sel_hi:[1,0]
	v_mul_f32_e32 v55, 0x45800000, v54
	v_cndmask_b32_e32 v54, v54, v55, vcc
	v_pk_mul_f32 v[38:39], v[38:39], v[54:55] op_sel_hi:[1,0]
	v_pk_mul_f32 v[36:37], v[36:37], v[54:55] op_sel_hi:[1,0]
	v_pk_mul_f32 v[38:39], v[2:3], v[38:39]
	v_pk_mul_f32 v[36:37], v[0:1], v[36:37]
	v_pk_fma_f32 v[38:39], v[48:49], v[38:39], v[18:19]
	v_pk_fma_f32 v[36:37], v[50:51], v[36:37], v[16:17]
	v_pk_mul_f32 v[34:35], v[34:35], v[54:55] op_sel_hi:[1,0]
	v_cvt_pk_bf16_f32 v36, v36, v37
	v_cvt_pk_bf16_f32 v37, v38, v39
	v_pk_mul_f32 v[32:33], v[32:33], v[54:55] op_sel_hi:[1,0]
	global_store_dwordx2 v[52:53], v[36:37], off
	v_pk_mul_f32 v[32:33], v[4:5], v[32:33]
	v_pk_mul_f32 v[34:35], v[6:7], v[34:35]
	v_pk_add_f32 v[36:37], v[46:47], 1.0 op_sel_hi:[1,0]
	v_pk_add_f32 v[38:39], v[44:45], 1.0 op_sel_hi:[1,0]
	v_pk_fma_f32 v[34:35], v[36:37], v[34:35], v[42:43]
	v_pk_fma_f32 v[32:33], v[38:39], v[32:33], v[40:41]
	v_pk_mul_f32 v[30:31], v[30:31], v[54:55] op_sel_hi:[1,0]
	v_cvt_pk_bf16_f32 v32, v32, v33
	v_cvt_pk_bf16_f32 v33, v34, v35
	v_pk_mul_f32 v[28:29], v[28:29], v[54:55] op_sel_hi:[1,0]
	global_store_dwordx2 v[52:53], v[32:33], off offset:512
	v_pk_mul_f32 v[28:29], v[8:9], v[28:29]
	v_pk_mul_f32 v[30:31], v[10:11], v[30:31]
	v_pk_add_f32 v[32:33], v[70:71], 1.0 op_sel_hi:[1,0]
	v_pk_add_f32 v[34:35], v[68:69], 1.0 op_sel_hi:[1,0]
	v_pk_fma_f32 v[30:31], v[32:33], v[30:31], v[66:67]
	v_pk_fma_f32 v[28:29], v[34:35], v[28:29], v[64:65]
	v_pk_mul_f32 v[26:27], v[26:27], v[54:55] op_sel_hi:[1,0]
	v_cvt_pk_bf16_f32 v28, v28, v29
	v_cvt_pk_bf16_f32 v29, v30, v31
	v_pk_mul_f32 v[24:25], v[24:25], v[54:55] op_sel_hi:[1,0]
	global_store_dwordx2 v[52:53], v[28:29], off offset:1024
	v_pk_mul_f32 v[24:25], v[12:13], v[24:25]
	v_pk_mul_f32 v[26:27], v[14:15], v[26:27]
	v_pk_add_f32 v[28:29], v[94:95], 1.0 op_sel_hi:[1,0]
	v_pk_add_f32 v[30:31], v[92:93], 1.0 op_sel_hi:[1,0]
	v_pk_fma_f32 v[26:27], v[28:29], v[26:27], v[90:91]
	v_pk_fma_f32 v[24:25], v[30:31], v[24:25], v[88:89]
	s_nop 0
	v_cvt_pk_bf16_f32 v24, v24, v25
	v_cvt_pk_bf16_f32 v25, v26, v27
	global_store_dwordx2 v[52:53], v[24:25], off offset:1536

.LBB0_111:
	s_or_b64 exec, exec, s[6:7]
	s_waitcnt vmcnt(23)
	v_mov_b32_e32 v174, v141
	s_waitcnt vmcnt(22)
	v_mov_b32_e32 v175, v137
	v_mov_b32_e32 v172, v140
	v_mov_b32_e32 v173, v136
	v_pk_mul_f32 v[174:175], v[174:175], v[174:175]
	s_waitcnt vmcnt(21)
	v_mov_b32_e32 v186, v133
	v_pk_fma_f32 v[172:173], v[172:173], v[172:173], v[174:175]
	v_mov_b32_e32 v174, v142
	v_mov_b32_e32 v175, v138
	v_pk_fma_f32 v[172:173], v[174:175], v[174:175], v[172:173]
	v_mov_b32_e32 v174, v143
	v_mov_b32_e32 v175, v139
	s_waitcnt vmcnt(20)
	v_mov_b32_e32 v187, v129
	v_pk_fma_f32 v[172:173], v[174:175], v[174:175], v[172:173]
	v_mov_b32_e32 v174, v132
	v_mov_b32_e32 v175, v128
	v_pk_mul_f32 v[186:187], v[186:187], v[186:187]
	v_add_f32_e32 v145, v172, v173
	v_pk_fma_f32 v[174:175], v[174:175], v[174:175], v[186:187]
	v_mov_b32_e32 v186, v134
	v_mov_b32_e32 v187, v130
	v_pk_fma_f32 v[174:175], v[186:187], v[186:187], v[174:175]
	v_mov_b32_e32 v186, v135
	v_mov_b32_e32 v187, v131
	v_pk_fma_f32 v[174:175], v[186:187], v[186:187], v[174:175]
	v_pk_add_f32 v[172:173], v[22:23], 1.0 op_sel_hi:[1,0]
	v_add_f32_e32 v145, v145, v174
	v_add_f32_e32 v145, v145, v175
	ds_bpermute_b32 v163, v178, v145
	v_pk_add_f32 v[174:175], v[20:21], 1.0 op_sel_hi:[1,0]
	s_waitcnt lgkmcnt(0)
	v_add_f32_e32 v145, v145, v163
	ds_bpermute_b32 v163, v179, v145
	s_waitcnt lgkmcnt(0)
	v_add_f32_e32 v145, v145, v163
	s_nop 1
	v_add_f32_dpp v145, v145, v145 row_ror:8 row_mask:0xf bank_mask:0xf
	s_nop 1
	v_add_f32_dpp v145, v145, v145 row_ror:4 row_mask:0xf bank_mask:0xf
	s_nop 1
	v_add_f32_dpp v163, v145, v145 quad_perm:[2,3,0,1] row_mask:0xf bank_mask:0xf
	v_ashrrev_i32_e32 v145, 31, v144
	v_lshlrev_b64 v[186:187], 11, v[144:145]
	v_lshl_add_u64 v[186:187], v[148:149], 0, v[186:187]
	s_nop 1
	v_add_f32_dpp v163, v163, v163 quad_perm:[1,0,3,2] row_mask:0xf bank_mask:0xf
	v_fmamk_f32 v163, v163, 0x3a800000, v184
	v_mul_f32_e32 v165, 0x4b800000, v163
	v_cmp_gt_f32_e32 vcc, s14, v163
	s_nop 1
	v_cndmask_b32_e32 v163, v163, v165, vcc
	v_rsq_f32_e32 v163, v163
	s_nop 0
	v_mul_f32_e32 v145, 0x45800000, v163
	v_cndmask_b32_e32 v188, v163, v145, vcc
	v_pk_mul_f32 v[142:143], v[142:143], v[188:189] op_sel_hi:[1,0]
	v_pk_mul_f32 v[140:141], v[140:141], v[188:189] op_sel_hi:[1,0]
	v_pk_mul_f32 v[142:143], v[2:3], v[142:143]
	v_pk_mul_f32 v[140:141], v[0:1], v[140:141]
	v_pk_fma_f32 v[142:143], v[172:173], v[142:143], v[18:19]
	v_pk_fma_f32 v[140:141], v[174:175], v[140:141], v[16:17]
	v_pk_mul_f32 v[138:139], v[138:139], v[188:189] op_sel_hi:[1,0]
	v_cvt_pk_bf16_f32 v140, v140, v141
	v_cvt_pk_bf16_f32 v141, v142, v143
	v_pk_mul_f32 v[136:137], v[136:137], v[188:189] op_sel_hi:[1,0]
	global_store_dwordx2 v[186:187], v[140:141], off
	v_pk_mul_f32 v[140:141], v[4:5], v[136:137]
	v_pk_mul_f32 v[142:143], v[6:7], v[138:139]
	v_pk_add_f32 v[136:137], v[46:47], 1.0 op_sel_hi:[1,0]
	v_pk_add_f32 v[138:139], v[44:45], 1.0 op_sel_hi:[1,0]
	v_pk_fma_f32 v[142:143], v[136:137], v[142:143], v[42:43]
	v_pk_fma_f32 v[140:141], v[138:139], v[140:141], v[40:41]
	v_pk_mul_f32 v[134:135], v[134:135], v[188:189] op_sel_hi:[1,0]
	v_cvt_pk_bf16_f32 v140, v140, v141
	v_cvt_pk_bf16_f32 v141, v142, v143
	v_pk_mul_f32 v[132:133], v[132:133], v[188:189] op_sel_hi:[1,0]
	global_store_dwordx2 v[186:187], v[140:141], off offset:512
	v_pk_mul_f32 v[140:141], v[8:9], v[132:133]
	v_pk_mul_f32 v[142:143], v[10:11], v[134:135]
	v_pk_add_f32 v[132:133], v[70:71], 1.0 op_sel_hi:[1,0]
	v_pk_add_f32 v[134:135], v[68:69], 1.0 op_sel_hi:[1,0]
	v_pk_fma_f32 v[142:143], v[132:133], v[142:143], v[66:67]
	v_pk_fma_f32 v[140:141], v[134:135], v[140:141], v[64:65]
	v_pk_mul_f32 v[130:131], v[130:131], v[188:189] op_sel_hi:[1,0]
	v_cvt_pk_bf16_f32 v140, v140, v141
	v_cvt_pk_bf16_f32 v141, v142, v143
	v_pk_mul_f32 v[128:129], v[128:129], v[188:189] op_sel_hi:[1,0]
	global_store_dwordx2 v[186:187], v[140:141], off offset:1024
	v_pk_mul_f32 v[140:141], v[12:13], v[128:129]
	v_pk_mul_f32 v[142:143], v[14:15], v[130:131]
	v_pk_add_f32 v[128:129], v[94:95], 1.0 op_sel_hi:[1,0]
	v_pk_add_f32 v[130:131], v[92:93], 1.0 op_sel_hi:[1,0]
	v_pk_fma_f32 v[142:143], v[128:129], v[142:143], v[90:91]
	v_pk_fma_f32 v[140:141], v[130:131], v[140:141], v[88:89]
	v_cmp_lt_i32_e32 vcc, v170, v176
	v_cvt_pk_bf16_f32 v140, v140, v141
	v_cvt_pk_bf16_f32 v141, v142, v143
	global_store_dwordx2 v[186:187], v[140:141], off offset:1536
	s_and_saveexec_b64 s[6:7], vcc
	s_cbranch_execz .LBB0_136
	v_add_u32_e32 v140, 0xffffe001, v144
	v_ashrrev_i32_e32 v140, 10, v140
	v_add_u32_e32 v140, 1, v140
	v_cmp_lt_i32_e32 vcc, s15, v144
	s_nop 1
	v_cndmask_b32_e32 v140, 0, v140, vcc
	v_cmp_ne_u32_e32 vcc, v140, v185
	s_and_saveexec_b64 s[8:9], vcc
	s_cbranch_execz .LBB0_122
	global_load_dwordx4 v[16:19], v[150:151], off
	global_load_dwordx4 v[20:23], v[152:153], off
	v_mad_i64_i32 v[128:129], s[10:11], v140, s3, v[160:161]
	s_mov_b64 s[10:11], 0

.LBB0_122:
	s_or_b64 exec, exec, s[8:9]
	s_waitcnt vmcnt(23)
	v_mov_b32_e32 v142, v125
	s_waitcnt vmcnt(22)
	v_mov_b32_e32 v143, v121
	v_mov_b32_e32 v140, v124
	v_mov_b32_e32 v141, v120
	v_pk_mul_f32 v[142:143], v[142:143], v[142:143]
	s_waitcnt vmcnt(21)
	v_mov_b32_e32 v186, v117
	v_pk_fma_f32 v[140:141], v[140:141], v[140:141], v[142:143]
	v_mov_b32_e32 v142, v126
	v_mov_b32_e32 v143, v122
	v_pk_fma_f32 v[140:141], v[142:143], v[142:143], v[140:141]
	v_mov_b32_e32 v142, v127
	v_mov_b32_e32 v143, v123
	s_waitcnt vmcnt(20)
	v_mov_b32_e32 v187, v113
	v_pk_fma_f32 v[140:141], v[142:143], v[142:143], v[140:141]
	v_mov_b32_e32 v142, v116
	v_mov_b32_e32 v143, v112
	v_pk_mul_f32 v[186:187], v[186:187], v[186:187]
	v_add_f32_e32 v140, v140, v141
	v_pk_fma_f32 v[142:143], v[142:143], v[142:143], v[186:187]
	v_mov_b32_e32 v186, v118
	v_mov_b32_e32 v187, v114
	v_pk_fma_f32 v[142:143], v[186:187], v[186:187], v[142:143]
	v_mov_b32_e32 v186, v119
	v_mov_b32_e32 v187, v115
	v_pk_fma_f32 v[142:143], v[186:187], v[186:187], v[142:143]
	v_ashrrev_i32_e32 v171, 31, v170
	v_add_f32_e32 v140, v140, v142
	v_add_f32_e32 v140, v140, v143
	ds_bpermute_b32 v141, v178, v140
	s_waitcnt lgkmcnt(0)
	v_add_f32_e32 v140, v140, v141
	ds_bpermute_b32 v141, v179, v140
	s_waitcnt lgkmcnt(0)
	v_add_f32_e32 v140, v140, v141
	s_nop 1
	v_add_f32_dpp v140, v140, v140 row_ror:8 row_mask:0xf bank_mask:0xf
	s_nop 1
	v_add_f32_dpp v140, v140, v140 row_ror:4 row_mask:0xf bank_mask:0xf
	s_nop 1
	v_add_f32_dpp v140, v140, v140 quad_perm:[2,3,0,1] row_mask:0xf bank_mask:0xf
	s_nop 1
	v_add_f32_dpp v140, v140, v140 quad_perm:[1,0,3,2] row_mask:0xf bank_mask:0xf
	v_fmamk_f32 v140, v140, 0x3a800000, v184
	v_mul_f32_e32 v141, 0x4b800000, v140
	v_cmp_gt_f32_e32 vcc, s14, v140
	s_nop 1
	v_cndmask_b32_e32 v140, v140, v141, vcc
	v_rsq_f32_e32 v142, v140
	v_lshlrev_b64 v[140:141], 11, v[170:171]
	v_lshl_add_u64 v[140:141], v[148:149], 0, v[140:141]
	v_mul_f32_e32 v143, 0x45800000, v142
	v_cndmask_b32_e32 v142, v142, v143, vcc
	v_pk_mul_f32 v[126:127], v[126:127], v[142:143] op_sel_hi:[1,0]
	v_pk_mul_f32 v[124:125], v[124:125], v[142:143] op_sel_hi:[1,0]
	v_pk_mul_f32 v[122:123], v[122:123], v[142:143] op_sel_hi:[1,0]
	v_pk_mul_f32 v[120:121], v[120:121], v[142:143] op_sel_hi:[1,0]
	v_pk_mul_f32 v[118:119], v[118:119], v[142:143] op_sel_hi:[1,0]
	v_pk_mul_f32 v[116:117], v[116:117], v[142:143] op_sel_hi:[1,0]
	v_pk_mul_f32 v[114:115], v[114:115], v[142:143] op_sel_hi:[1,0]
	v_pk_mul_f32 v[112:113], v[112:113], v[142:143] op_sel_hi:[1,0]
	v_pk_mul_f32 v[124:125], v[0:1], v[124:125]
	v_pk_mul_f32 v[126:127], v[2:3], v[126:127]
	v_pk_mul_f32 v[120:121], v[4:5], v[120:121]
	v_pk_mul_f32 v[122:123], v[6:7], v[122:123]
	v_pk_mul_f32 v[116:117], v[8:9], v[116:117]
	v_pk_mul_f32 v[118:119], v[10:11], v[118:119]
	v_pk_mul_f32 v[112:113], v[12:13], v[112:113]
	v_pk_mul_f32 v[114:115], v[14:15], v[114:115]
	v_pk_fma_f32 v[126:127], v[172:173], v[126:127], v[18:19]
	v_pk_fma_f32 v[124:125], v[174:175], v[124:125], v[16:17]
	v_pk_fma_f32 v[122:123], v[136:137], v[122:123], v[42:43]
	v_pk_fma_f32 v[120:121], v[138:139], v[120:121], v[40:41]
	v_pk_fma_f32 v[118:119], v[132:133], v[118:119], v[66:67]
	v_pk_fma_f32 v[116:117], v[134:135], v[116:117], v[64:65]
	v_pk_fma_f32 v[114:115], v[128:129], v[114:115], v[90:91]
	v_pk_fma_f32 v[112:113], v[130:131], v[112:113], v[88:89]
	v_cvt_pk_bf16_f32 v124, v124, v125
	v_cvt_pk_bf16_f32 v125, v126, v127
	v_cvt_pk_bf16_f32 v120, v120, v121
	v_cvt_pk_bf16_f32 v121, v122, v123
	v_cvt_pk_bf16_f32 v116, v116, v117
	v_cvt_pk_bf16_f32 v117, v118, v119
	v_cvt_pk_bf16_f32 v112, v112, v113
	v_cvt_pk_bf16_f32 v113, v114, v115
	global_store_dwordx2 v[140:141], v[124:125], off
	global_store_dwordx2 v[140:141], v[120:121], off offset:512
	global_store_dwordx2 v[140:141], v[116:117], off offset:1024
	global_store_dwordx2 v[140:141], v[112:113], off offset:1536
	s_or_b64 exec, exec, s[6:7]
	v_cmp_lt_i32_e32 vcc, v168, v176
	s_and_saveexec_b64 s[6:7], vcc
	s_cbranch_execnz .LBB0_137

.LBB0_134:
	s_or_b64 exec, exec, s[8:9]
	s_waitcnt vmcnt(15)
	v_mov_b32_e32 v98, v85
	s_waitcnt vmcnt(14)
	v_mov_b32_e32 v99, v81
	v_mov_b32_e32 v96, v84
	v_mov_b32_e32 v97, v80
	v_pk_mul_f32 v[98:99], v[98:99], v[98:99]
	s_waitcnt vmcnt(13)
	v_mov_b32_e32 v100, v77
	v_pk_fma_f32 v[96:97], v[96:97], v[96:97], v[98:99]
	v_mov_b32_e32 v98, v86
	v_mov_b32_e32 v99, v82
	v_pk_fma_f32 v[96:97], v[98:99], v[98:99], v[96:97]
	v_mov_b32_e32 v98, v87
	v_mov_b32_e32 v99, v83
	s_waitcnt vmcnt(12)
	v_mov_b32_e32 v101, v73
	v_pk_fma_f32 v[96:97], v[98:99], v[98:99], v[96:97]
	v_mov_b32_e32 v98, v76
	v_mov_b32_e32 v99, v72
	v_pk_mul_f32 v[100:101], v[100:101], v[100:101]
	v_add_f32_e32 v96, v96, v97
	v_pk_fma_f32 v[98:99], v[98:99], v[98:99], v[100:101]
	v_mov_b32_e32 v100, v78
	v_mov_b32_e32 v101, v74
	v_pk_fma_f32 v[98:99], v[100:101], v[100:101], v[98:99]
	v_mov_b32_e32 v100, v79
	v_mov_b32_e32 v101, v75
	v_pk_fma_f32 v[98:99], v[100:101], v[100:101], v[98:99]
	v_ashrrev_i32_e32 v167, 31, v166
	v_add_f32_e32 v96, v96, v98
	v_add_f32_e32 v96, v96, v99
	ds_bpermute_b32 v97, v178, v96
	v_lshlrev_b64 v[100:101], 11, v[166:167]
	v_lshl_add_u64 v[100:101], v[148:149], 0, v[100:101]
	s_waitcnt lgkmcnt(0)
	v_add_f32_e32 v96, v96, v97
	ds_bpermute_b32 v97, v179, v96
	s_waitcnt lgkmcnt(0)
	v_add_f32_e32 v96, v96, v97
	s_nop 1
	v_add_f32_dpp v96, v96, v96 row_ror:8 row_mask:0xf bank_mask:0xf
	s_nop 1
	v_add_f32_dpp v96, v96, v96 row_ror:4 row_mask:0xf bank_mask:0xf
	s_nop 1
	v_add_f32_dpp v98, v96, v96 quad_perm:[2,3,0,1] row_mask:0xf bank_mask:0xf
	v_pk_add_f32 v[96:97], v[22:23], 1.0 op_sel_hi:[1,0]
	s_nop 1
	v_add_f32_dpp v98, v98, v98 quad_perm:[1,0,3,2] row_mask:0xf bank_mask:0xf
	v_fmamk_f32 v98, v98, 0x3a800000, v184
	v_mul_f32_e32 v99, 0x4b800000, v98
	v_cmp_gt_f32_e32 vcc, s14, v98
	s_nop 1
	v_cndmask_b32_e32 v98, v98, v99, vcc
	v_rsq_f32_e32 v102, v98
	v_pk_add_f32 v[98:99], v[20:21], 1.0 op_sel_hi:[1,0]
	v_mul_f32_e32 v103, 0x45800000, v102
	v_cndmask_b32_e32 v102, v102, v103, vcc
	v_pk_mul_f32 v[86:87], v[86:87], v[102:103] op_sel_hi:[1,0]
	v_pk_mul_f32 v[84:85], v[84:85], v[102:103] op_sel_hi:[1,0]
	v_pk_mul_f32 v[86:87], v[2:3], v[86:87]
	v_pk_mul_f32 v[84:85], v[0:1], v[84:85]
	v_pk_fma_f32 v[86:87], v[96:97], v[86:87], v[18:19]
	v_pk_fma_f32 v[84:85], v[98:99], v[84:85], v[16:17]
	v_pk_mul_f32 v[82:83], v[82:83], v[102:103] op_sel_hi:[1,0]
	v_cvt_pk_bf16_f32 v84, v84, v85
	v_cvt_pk_bf16_f32 v85, v86, v87
	v_pk_mul_f32 v[80:81], v[80:81], v[102:103] op_sel_hi:[1,0]
	global_store_dwordx2 v[100:101], v[84:85], off
	v_pk_mul_f32 v[80:81], v[4:5], v[80:81]
	v_pk_mul_f32 v[82:83], v[6:7], v[82:83]
	v_pk_add_f32 v[84:85], v[46:47], 1.0 op_sel_hi:[1,0]
	v_pk_add_f32 v[86:87], v[44:45], 1.0 op_sel_hi:[1,0]
	v_pk_fma_f32 v[82:83], v[84:85], v[82:83], v[42:43]
	v_pk_fma_f32 v[80:81], v[86:87], v[80:81], v[40:41]
	v_pk_mul_f32 v[78:79], v[78:79], v[102:103] op_sel_hi:[1,0]
	v_cvt_pk_bf16_f32 v80, v80, v81
	v_cvt_pk_bf16_f32 v81, v82, v83
	v_pk_mul_f32 v[76:77], v[76:77], v[102:103] op_sel_hi:[1,0]
	global_store_dwordx2 v[100:101], v[80:81], off offset:512
	v_pk_mul_f32 v[76:77], v[8:9], v[76:77]
	v_pk_mul_f32 v[78:79], v[10:11], v[78:79]
	v_pk_add_f32 v[80:81], v[70:71], 1.0 op_sel_hi:[1,0]
	v_pk_add_f32 v[82:83], v[68:69], 1.0 op_sel_hi:[1,0]
	v_pk_fma_f32 v[78:79], v[80:81], v[78:79], v[66:67]
	v_pk_fma_f32 v[76:77], v[82:83], v[76:77], v[64:65]
	v_pk_mul_f32 v[74:75], v[74:75], v[102:103] op_sel_hi:[1,0]
	v_cvt_pk_bf16_f32 v76, v76, v77
	v_cvt_pk_bf16_f32 v77, v78, v79
	v_pk_mul_f32 v[72:73], v[72:73], v[102:103] op_sel_hi:[1,0]
	global_store_dwordx2 v[100:101], v[76:77], off offset:1024
	v_pk_mul_f32 v[72:73], v[12:13], v[72:73]
	v_pk_mul_f32 v[74:75], v[14:15], v[74:75]
	v_pk_add_f32 v[76:77], v[94:95], 1.0 op_sel_hi:[1,0]
	v_pk_add_f32 v[78:79], v[92:93], 1.0 op_sel_hi:[1,0]
	v_pk_fma_f32 v[74:75], v[76:77], v[74:75], v[90:91]
	v_pk_fma_f32 v[72:73], v[78:79], v[72:73], v[88:89]
	s_nop 0
	v_cvt_pk_bf16_f32 v72, v72, v73
	v_cvt_pk_bf16_f32 v73, v74, v75
	global_store_dwordx2 v[100:101], v[72:73], off offset:1536
	s_or_b64 exec, exec, s[6:7]
	v_cmp_lt_i32_e32 vcc, v164, v176
	s_and_saveexec_b64 s[6:7], vcc
	s_cbranch_execnz .LBB0_149

.LBB0_147:
	s_or_b64 exec, exec, s[8:9]
	s_waitcnt vmcnt(19)
	v_mov_b32_e32 v114, v109
	s_waitcnt vmcnt(18)
	v_mov_b32_e32 v115, v105
	v_mov_b32_e32 v112, v108
	v_mov_b32_e32 v113, v104
	v_pk_mul_f32 v[114:115], v[114:115], v[114:115]
	s_waitcnt vmcnt(17)
	v_mov_b32_e32 v116, v101
	v_pk_fma_f32 v[112:113], v[112:113], v[112:113], v[114:115]
	v_mov_b32_e32 v114, v110
	v_mov_b32_e32 v115, v106
	v_pk_fma_f32 v[112:113], v[114:115], v[114:115], v[112:113]
	v_mov_b32_e32 v114, v111
	v_mov_b32_e32 v115, v107
	s_waitcnt vmcnt(16)
	v_mov_b32_e32 v117, v97
	v_pk_fma_f32 v[112:113], v[114:115], v[114:115], v[112:113]
	v_mov_b32_e32 v114, v100
	v_mov_b32_e32 v115, v96
	v_pk_mul_f32 v[116:117], v[116:117], v[116:117]
	v_add_f32_e32 v112, v112, v113
	v_pk_fma_f32 v[114:115], v[114:115], v[114:115], v[116:117]
	v_mov_b32_e32 v116, v102
	v_mov_b32_e32 v117, v98
	v_pk_fma_f32 v[114:115], v[116:117], v[116:117], v[114:115]
	v_mov_b32_e32 v116, v103
	v_mov_b32_e32 v117, v99
	v_pk_fma_f32 v[114:115], v[116:117], v[116:117], v[114:115]
	v_ashrrev_i32_e32 v169, 31, v168
	v_add_f32_e32 v112, v112, v114
	v_add_f32_e32 v112, v112, v115
	ds_bpermute_b32 v113, v178, v112
	v_lshlrev_b64 v[116:117], 11, v[168:169]
	v_lshl_add_u64 v[116:117], v[148:149], 0, v[116:117]
	s_waitcnt lgkmcnt(0)
	v_add_f32_e32 v112, v112, v113
	ds_bpermute_b32 v113, v179, v112
	s_waitcnt lgkmcnt(0)
	v_add_f32_e32 v112, v112, v113
	s_nop 1
	v_add_f32_dpp v112, v112, v112 row_ror:8 row_mask:0xf bank_mask:0xf
	s_nop 1
	v_add_f32_dpp v112, v112, v112 row_ror:4 row_mask:0xf bank_mask:0xf
	s_nop 1
	v_add_f32_dpp v114, v112, v112 quad_perm:[2,3,0,1] row_mask:0xf bank_mask:0xf
	v_pk_add_f32 v[112:113], v[22:23], 1.0 op_sel_hi:[1,0]
	s_nop 1
	v_add_f32_dpp v114, v114, v114 quad_perm:[1,0,3,2] row_mask:0xf bank_mask:0xf
	v_fmamk_f32 v114, v114, 0x3a800000, v184
	v_mul_f32_e32 v115, 0x4b800000, v114
	v_cmp_gt_f32_e32 vcc, s14, v114
	s_nop 1
	v_cndmask_b32_e32 v114, v114, v115, vcc
	v_rsq_f32_e32 v118, v114
	v_pk_add_f32 v[114:115], v[20:21], 1.0 op_sel_hi:[1,0]
	v_mul_f32_e32 v119, 0x45800000, v118
	v_cndmask_b32_e32 v118, v118, v119, vcc
	v_pk_mul_f32 v[110:111], v[110:111], v[118:119] op_sel_hi:[1,0]
	v_pk_mul_f32 v[108:109], v[108:109], v[118:119] op_sel_hi:[1,0]
	v_pk_mul_f32 v[110:111], v[2:3], v[110:111]
	v_pk_mul_f32 v[108:109], v[0:1], v[108:109]
	v_pk_fma_f32 v[110:111], v[112:113], v[110:111], v[18:19]
	v_pk_fma_f32 v[108:109], v[114:115], v[108:109], v[16:17]
	v_pk_mul_f32 v[106:107], v[106:107], v[118:119] op_sel_hi:[1,0]
	v_cvt_pk_bf16_f32 v108, v108, v109
	v_cvt_pk_bf16_f32 v109, v110, v111
	v_pk_mul_f32 v[104:105], v[104:105], v[118:119] op_sel_hi:[1,0]
	global_store_dwordx2 v[116:117], v[108:109], off
	v_pk_mul_f32 v[104:105], v[4:5], v[104:105]
	v_pk_mul_f32 v[106:107], v[6:7], v[106:107]
	v_pk_add_f32 v[108:109], v[46:47], 1.0 op_sel_hi:[1,0]
	v_pk_add_f32 v[110:111], v[44:45], 1.0 op_sel_hi:[1,0]
	v_pk_fma_f32 v[106:107], v[108:109], v[106:107], v[42:43]
	v_pk_fma_f32 v[104:105], v[110:111], v[104:105], v[40:41]
	v_pk_mul_f32 v[102:103], v[102:103], v[118:119] op_sel_hi:[1,0]
	v_cvt_pk_bf16_f32 v104, v104, v105
	v_cvt_pk_bf16_f32 v105, v106, v107
	v_pk_mul_f32 v[100:101], v[100:101], v[118:119] op_sel_hi:[1,0]
	global_store_dwordx2 v[116:117], v[104:105], off offset:512
	v_pk_mul_f32 v[100:101], v[8:9], v[100:101]
	v_pk_mul_f32 v[102:103], v[10:11], v[102:103]
	v_pk_add_f32 v[104:105], v[70:71], 1.0 op_sel_hi:[1,0]
	v_pk_add_f32 v[106:107], v[68:69], 1.0 op_sel_hi:[1,0]
	v_pk_fma_f32 v[102:103], v[104:105], v[102:103], v[66:67]
	v_pk_fma_f32 v[100:101], v[106:107], v[100:101], v[64:65]
	v_pk_mul_f32 v[98:99], v[98:99], v[118:119] op_sel_hi:[1,0]
	v_cvt_pk_bf16_f32 v100, v100, v101
	v_cvt_pk_bf16_f32 v101, v102, v103
	v_pk_mul_f32 v[96:97], v[96:97], v[118:119] op_sel_hi:[1,0]
	global_store_dwordx2 v[116:117], v[100:101], off offset:1024
	v_pk_mul_f32 v[96:97], v[12:13], v[96:97]
	v_pk_mul_f32 v[98:99], v[14:15], v[98:99]
	v_pk_add_f32 v[100:101], v[94:95], 1.0 op_sel_hi:[1,0]
	v_pk_add_f32 v[102:103], v[92:93], 1.0 op_sel_hi:[1,0]
	v_pk_fma_f32 v[98:99], v[100:101], v[98:99], v[90:91]
	v_pk_fma_f32 v[96:97], v[102:103], v[96:97], v[88:89]
	s_nop 0
	v_cvt_pk_bf16_f32 v96, v96, v97
	v_cvt_pk_bf16_f32 v97, v98, v99
	global_store_dwordx2 v[116:117], v[96:97], off offset:1536
	s_or_b64 exec, exec, s[6:7]
	v_cmp_lt_i32_e32 vcc, v166, v176
	s_and_saveexec_b64 s[6:7], vcc
	s_cbranch_execnz .LBB0_124

.LBB0_159:
	s_or_b64 exec, exec, s[8:9]
	s_waitcnt vmcnt(11)
	v_mov_b32_e32 v74, v61
	s_waitcnt vmcnt(10)
	v_mov_b32_e32 v75, v57
	v_mov_b32_e32 v72, v60
	v_mov_b32_e32 v73, v56
	v_pk_mul_f32 v[74:75], v[74:75], v[74:75]
	s_waitcnt vmcnt(9)
	v_mov_b32_e32 v76, v53
	v_pk_fma_f32 v[72:73], v[72:73], v[72:73], v[74:75]
	v_mov_b32_e32 v74, v62
	v_mov_b32_e32 v75, v58
	v_pk_fma_f32 v[72:73], v[74:75], v[74:75], v[72:73]
	v_mov_b32_e32 v74, v63
	v_mov_b32_e32 v75, v59
	s_waitcnt vmcnt(8)
	v_mov_b32_e32 v77, v49
	v_pk_fma_f32 v[72:73], v[74:75], v[74:75], v[72:73]
	v_mov_b32_e32 v74, v52
	v_mov_b32_e32 v75, v48
	v_pk_mul_f32 v[76:77], v[76:77], v[76:77]
	v_add_f32_e32 v72, v72, v73
	v_pk_fma_f32 v[74:75], v[74:75], v[74:75], v[76:77]
	v_mov_b32_e32 v76, v54
	v_mov_b32_e32 v77, v50
	v_pk_fma_f32 v[74:75], v[76:77], v[76:77], v[74:75]
	v_mov_b32_e32 v76, v55
	v_mov_b32_e32 v77, v51
	v_pk_fma_f32 v[74:75], v[76:77], v[76:77], v[74:75]
	v_ashrrev_i32_e32 v165, 31, v164
	v_add_f32_e32 v72, v72, v74
	v_add_f32_e32 v72, v72, v75
	ds_bpermute_b32 v73, v178, v72
	v_lshlrev_b64 v[76:77], 11, v[164:165]
	v_lshl_add_u64 v[76:77], v[148:149], 0, v[76:77]
	s_waitcnt lgkmcnt(0)
	v_add_f32_e32 v72, v72, v73
	ds_bpermute_b32 v73, v179, v72
	s_waitcnt lgkmcnt(0)
	v_add_f32_e32 v72, v72, v73
	s_nop 1
	v_add_f32_dpp v72, v72, v72 row_ror:8 row_mask:0xf bank_mask:0xf
	s_nop 1
	v_add_f32_dpp v72, v72, v72 row_ror:4 row_mask:0xf bank_mask:0xf
	s_nop 1
	v_add_f32_dpp v74, v72, v72 quad_perm:[2,3,0,1] row_mask:0xf bank_mask:0xf
	v_pk_add_f32 v[72:73], v[22:23], 1.0 op_sel_hi:[1,0]
	s_nop 1
	v_add_f32_dpp v74, v74, v74 quad_perm:[1,0,3,2] row_mask:0xf bank_mask:0xf
	v_fmamk_f32 v74, v74, 0x3a800000, v184
	v_mul_f32_e32 v75, 0x4b800000, v74
	v_cmp_gt_f32_e32 vcc, s14, v74
	s_nop 1
	v_cndmask_b32_e32 v74, v74, v75, vcc
	v_rsq_f32_e32 v78, v74
	v_pk_add_f32 v[74:75], v[20:21], 1.0 op_sel_hi:[1,0]
	v_mul_f32_e32 v79, 0x45800000, v78
	v_cndmask_b32_e32 v78, v78, v79, vcc
	v_pk_mul_f32 v[62:63], v[62:63], v[78:79] op_sel_hi:[1,0]
	v_pk_mul_f32 v[60:61], v[60:61], v[78:79] op_sel_hi:[1,0]
	v_pk_mul_f32 v[62:63], v[2:3], v[62:63]
	v_pk_mul_f32 v[60:61], v[0:1], v[60:61]
	v_pk_fma_f32 v[62:63], v[72:73], v[62:63], v[18:19]
	v_pk_fma_f32 v[60:61], v[74:75], v[60:61], v[16:17]
	v_pk_mul_f32 v[58:59], v[58:59], v[78:79] op_sel_hi:[1,0]
	v_cvt_pk_bf16_f32 v60, v60, v61
	v_cvt_pk_bf16_f32 v61, v62, v63
	v_pk_mul_f32 v[56:57], v[56:57], v[78:79] op_sel_hi:[1,0]
	global_store_dwordx2 v[76:77], v[60:61], off
	v_pk_mul_f32 v[56:57], v[4:5], v[56:57]
	v_pk_mul_f32 v[58:59], v[6:7], v[58:59]
	v_pk_add_f32 v[60:61], v[46:47], 1.0 op_sel_hi:[1,0]
	v_pk_add_f32 v[62:63], v[44:45], 1.0 op_sel_hi:[1,0]
	v_pk_fma_f32 v[58:59], v[60:61], v[58:59], v[42:43]
	v_pk_fma_f32 v[56:57], v[62:63], v[56:57], v[40:41]
	v_pk_mul_f32 v[54:55], v[54:55], v[78:79] op_sel_hi:[1,0]
	v_cvt_pk_bf16_f32 v56, v56, v57
	v_cvt_pk_bf16_f32 v57, v58, v59
	v_pk_mul_f32 v[52:53], v[52:53], v[78:79] op_sel_hi:[1,0]
	global_store_dwordx2 v[76:77], v[56:57], off offset:512
	v_pk_mul_f32 v[52:53], v[8:9], v[52:53]
	v_pk_mul_f32 v[54:55], v[10:11], v[54:55]
	v_pk_add_f32 v[56:57], v[70:71], 1.0 op_sel_hi:[1,0]
	v_pk_add_f32 v[58:59], v[68:69], 1.0 op_sel_hi:[1,0]
	v_pk_fma_f32 v[54:55], v[56:57], v[54:55], v[66:67]
	v_pk_fma_f32 v[52:53], v[58:59], v[52:53], v[64:65]
	v_pk_mul_f32 v[50:51], v[50:51], v[78:79] op_sel_hi:[1,0]
	v_cvt_pk_bf16_f32 v52, v52, v53
	v_cvt_pk_bf16_f32 v53, v54, v55
	v_pk_mul_f32 v[48:49], v[48:49], v[78:79] op_sel_hi:[1,0]
	global_store_dwordx2 v[76:77], v[52:53], off offset:1024
	v_pk_mul_f32 v[48:49], v[12:13], v[48:49]
	v_pk_mul_f32 v[50:51], v[14:15], v[50:51]
	v_pk_add_f32 v[52:53], v[94:95], 1.0 op_sel_hi:[1,0]
	v_pk_add_f32 v[54:55], v[92:93], 1.0 op_sel_hi:[1,0]
	v_pk_fma_f32 v[50:51], v[52:53], v[50:51], v[90:91]
	v_pk_fma_f32 v[48:49], v[54:55], v[48:49], v[88:89]
	s_nop 0
	v_cvt_pk_bf16_f32 v48, v48, v49
	v_cvt_pk_bf16_f32 v49, v50, v51
	global_store_dwordx2 v[76:77], v[48:49], off offset:1536
	s_or_b64 exec, exec, s[6:7]
	v_cmp_lt_i32_e32 vcc, v162, v176
	s_and_saveexec_b64 s[6:7], vcc
	s_cbranch_execz .LBB0_100

.LBB0_1130:
	s_or_b64 exec, exec, s[40:41]
	v_mov_b32_e32 v60, v45
	v_mov_b32_e32 v61, v41
	v_mov_b32_e32 v58, v44
	v_mov_b32_e32 v59, v40
	v_pk_mul_f32 v[60:61], v[60:61], v[60:61]
	v_mov_b32_e32 v62, v37
	v_pk_fma_f32 v[58:59], v[58:59], v[58:59], v[60:61]
	v_mov_b32_e32 v60, v46
	v_mov_b32_e32 v61, v42
	v_pk_fma_f32 v[58:59], v[60:61], v[60:61], v[58:59]
	v_mov_b32_e32 v60, v47
	v_mov_b32_e32 v61, v43
	v_mov_b32_e32 v63, v33
	v_pk_fma_f32 v[58:59], v[60:61], v[60:61], v[58:59]
	v_mov_b32_e32 v60, v36
	v_mov_b32_e32 v61, v32
	v_pk_mul_f32 v[62:63], v[62:63], v[62:63]
	v_add_f32_e32 v58, v58, v59
	v_pk_fma_f32 v[60:61], v[60:61], v[60:61], v[62:63]
	v_mov_b32_e32 v62, v38
	v_mov_b32_e32 v63, v34
	v_pk_fma_f32 v[60:61], v[62:63], v[62:63], v[60:61]
	v_mov_b32_e32 v62, v39
	v_mov_b32_e32 v63, v35
	v_pk_fma_f32 v[60:61], v[62:63], v[62:63], v[60:61]
	v_lshl_add_u64 v[56:57], v[132:133], 0, v[56:57]
	v_add_f32_e32 v58, v58, v60
	v_add_f32_e32 v58, v58, v61
	ds_bpermute_b32 v59, v228, v58
	v_pk_add_f32 v[60:61], v[20:21], 1.0 op_sel_hi:[1,0]
	s_waitcnt lgkmcnt(0)
	v_add_f32_e32 v58, v58, v59
	ds_bpermute_b32 v59, v229, v58
	s_waitcnt lgkmcnt(0)
	v_add_f32_e32 v58, v58, v59
	s_nop 1
	v_add_f32_dpp v58, v58, v58 row_ror:8 row_mask:0xf bank_mask:0xf
	s_nop 1
	v_add_f32_dpp v58, v58, v58 row_ror:4 row_mask:0xf bank_mask:0xf
	s_nop 1
	v_add_f32_dpp v58, v58, v58 quad_perm:[2,3,0,1] row_mask:0xf bank_mask:0xf
	s_nop 1
	v_add_f32_dpp v58, v58, v58 quad_perm:[1,0,3,2] row_mask:0xf bank_mask:0xf
	v_fmamk_f32 v58, v58, 0x3a800000, v234
	v_mul_f32_e32 v59, 0x4b800000, v58
	v_cmp_gt_f32_e32 vcc, s28, v58
	s_nop 1
	v_cndmask_b32_e32 v58, v58, v59, vcc
	v_rsq_f32_e32 v62, v58
	v_pk_add_f32 v[58:59], v[22:23], 1.0 op_sel_hi:[1,0]
	v_mul_f32_e32 v63, 0x45800000, v62
	v_cndmask_b32_e32 v62, v62, v63, vcc
	v_pk_mul_f32 v[46:47], v[46:47], v[62:63] op_sel_hi:[1,0]
	v_pk_mul_f32 v[44:45], v[44:45], v[62:63] op_sel_hi:[1,0]
	v_pk_mul_f32 v[46:47], v[10:11], v[46:47]
	v_pk_mul_f32 v[44:45], v[8:9], v[44:45]
	v_pk_fma_f32 v[46:47], v[58:59], v[46:47], v[18:19]
	v_pk_fma_f32 v[44:45], v[60:61], v[44:45], v[16:17]
	v_pk_mul_f32 v[42:43], v[42:43], v[62:63] op_sel_hi:[1,0]
	v_cvt_pk_bf16_f32 v44, v44, v45
	v_cvt_pk_bf16_f32 v45, v46, v47
	v_pk_mul_f32 v[40:41], v[40:41], v[62:63] op_sel_hi:[1,0]
	global_store_dwordx2 v[56:57], v[44:45], off
	v_pk_mul_f32 v[40:41], v[0:1], v[40:41]
	v_pk_mul_f32 v[42:43], v[2:3], v[42:43]
	v_pk_add_f32 v[44:45], v[30:31], 1.0 op_sel_hi:[1,0]
	v_pk_add_f32 v[46:47], v[28:29], 1.0 op_sel_hi:[1,0]
	v_pk_fma_f32 v[42:43], v[44:45], v[42:43], v[26:27]
	v_pk_fma_f32 v[40:41], v[46:47], v[40:41], v[24:25]
	v_pk_mul_f32 v[38:39], v[38:39], v[62:63] op_sel_hi:[1,0]
	v_cvt_pk_bf16_f32 v40, v40, v41
	v_cvt_pk_bf16_f32 v41, v42, v43
	v_pk_mul_f32 v[36:37], v[36:37], v[62:63] op_sel_hi:[1,0]
	global_store_dwordx2 v[56:57], v[40:41], off offset:512
	v_pk_mul_f32 v[36:37], v[4:5], v[36:37]
	v_pk_mul_f32 v[38:39], v[6:7], v[38:39]
	v_pk_add_f32 v[40:41], v[54:55], 1.0 op_sel_hi:[1,0]
	v_pk_add_f32 v[42:43], v[52:53], 1.0 op_sel_hi:[1,0]
	v_pk_fma_f32 v[38:39], v[40:41], v[38:39], v[50:51]
	v_pk_fma_f32 v[36:37], v[42:43], v[36:37], v[48:49]
	v_pk_mul_f32 v[34:35], v[34:35], v[62:63] op_sel_hi:[1,0]
	v_cvt_pk_bf16_f32 v36, v36, v37
	v_cvt_pk_bf16_f32 v37, v38, v39
	v_pk_mul_f32 v[32:33], v[32:33], v[62:63] op_sel_hi:[1,0]
	global_store_dwordx2 v[56:57], v[36:37], off offset:1024
	v_pk_mul_f32 v[32:33], v[12:13], v[32:33]
	v_pk_mul_f32 v[34:35], v[14:15], v[34:35]
	v_pk_add_f32 v[36:37], v[78:79], 1.0 op_sel_hi:[1,0]
	v_pk_add_f32 v[38:39], v[76:77], 1.0 op_sel_hi:[1,0]
	v_pk_fma_f32 v[34:35], v[36:37], v[34:35], v[74:75]
	v_pk_fma_f32 v[32:33], v[38:39], v[32:33], v[72:73]
	s_nop 0
	v_cvt_pk_bf16_f32 v32, v32, v33
	v_cvt_pk_bf16_f32 v33, v34, v35
	global_store_dwordx2 v[56:57], v[32:33], off offset:1536

.LBB0_1142:
	s_or_b64 exec, exec, s[6:7]
	v_mov_b32_e32 v236, v217
	v_mov_b32_e32 v237, v213
	v_mov_b32_e32 v222, v216
	v_mov_b32_e32 v223, v212
	v_pk_mul_f32 v[236:237], v[236:237], v[236:237]
	v_mov_b32_e32 v238, v209
	v_pk_fma_f32 v[222:223], v[222:223], v[222:223], v[236:237]
	v_mov_b32_e32 v236, v218
	v_mov_b32_e32 v237, v214
	v_pk_fma_f32 v[222:223], v[236:237], v[236:237], v[222:223]
	v_mov_b32_e32 v236, v219
	v_mov_b32_e32 v237, v215
	v_mov_b32_e32 v239, v205
	v_pk_fma_f32 v[222:223], v[236:237], v[236:237], v[222:223]
	v_mov_b32_e32 v236, v208
	v_mov_b32_e32 v237, v204
	v_pk_mul_f32 v[238:239], v[238:239], v[238:239]
	v_add_f32_e32 v129, v222, v223
	v_pk_fma_f32 v[236:237], v[236:237], v[236:237], v[238:239]
	v_mov_b32_e32 v238, v210
	v_mov_b32_e32 v239, v206
	v_pk_fma_f32 v[236:237], v[238:239], v[238:239], v[236:237]
	v_mov_b32_e32 v238, v211
	v_mov_b32_e32 v239, v207
	v_pk_fma_f32 v[236:237], v[238:239], v[238:239], v[236:237]
	v_pk_add_f32 v[222:223], v[20:21], 1.0 op_sel_hi:[1,0]
	v_add_f32_e32 v129, v129, v236
	v_add_f32_e32 v129, v129, v237
	ds_bpermute_b32 v155, v228, v129
	v_lshl_add_u64 v[236:237], v[132:133], 0, v[220:221]
	v_pk_add_f32 v[220:221], v[22:23], 1.0 op_sel_hi:[1,0]
	s_waitcnt lgkmcnt(0)
	v_add_f32_e32 v129, v129, v155
	ds_bpermute_b32 v155, v229, v129
	s_waitcnt lgkmcnt(0)
	v_add_f32_e32 v129, v129, v155
	s_nop 1
	v_add_f32_dpp v129, v129, v129 row_ror:8 row_mask:0xf bank_mask:0xf
	s_nop 1
	v_add_f32_dpp v129, v129, v129 row_ror:4 row_mask:0xf bank_mask:0xf
	s_nop 1
	v_add_f32_dpp v129, v129, v129 quad_perm:[2,3,0,1] row_mask:0xf bank_mask:0xf
	s_nop 1
	v_add_f32_dpp v129, v129, v129 quad_perm:[1,0,3,2] row_mask:0xf bank_mask:0xf
	v_fmamk_f32 v129, v129, 0x3a800000, v234
	v_mul_f32_e32 v155, 0x4b800000, v129
	v_cmp_gt_f32_e32 vcc, s28, v129
	s_nop 1
	v_cndmask_b32_e32 v129, v129, v155, vcc
	v_rsq_f32_e32 v129, v129
	s_nop 0
	v_mul_f32_e32 v155, 0x45800000, v129
	v_cndmask_b32_e32 v238, v129, v155, vcc
	v_pk_mul_f32 v[218:219], v[218:219], v[238:239] op_sel_hi:[1,0]
	v_pk_mul_f32 v[216:217], v[216:217], v[238:239] op_sel_hi:[1,0]
	v_pk_mul_f32 v[218:219], v[10:11], v[218:219]
	v_pk_mul_f32 v[216:217], v[8:9], v[216:217]
	v_pk_fma_f32 v[218:219], v[220:221], v[218:219], v[18:19]
	v_pk_fma_f32 v[216:217], v[222:223], v[216:217], v[16:17]
	v_pk_mul_f32 v[214:215], v[214:215], v[238:239] op_sel_hi:[1,0]
	v_cvt_pk_bf16_f32 v216, v216, v217
	v_cvt_pk_bf16_f32 v217, v218, v219
	v_pk_mul_f32 v[212:213], v[212:213], v[238:239] op_sel_hi:[1,0]
	global_store_dwordx2 v[236:237], v[216:217], off
	v_pk_mul_f32 v[216:217], v[0:1], v[212:213]
	v_pk_mul_f32 v[218:219], v[2:3], v[214:215]
	v_pk_add_f32 v[212:213], v[30:31], 1.0 op_sel_hi:[1,0]
	v_pk_add_f32 v[214:215], v[28:29], 1.0 op_sel_hi:[1,0]
	v_pk_fma_f32 v[218:219], v[212:213], v[218:219], v[26:27]
	v_pk_fma_f32 v[216:217], v[214:215], v[216:217], v[24:25]
	v_pk_mul_f32 v[210:211], v[210:211], v[238:239] op_sel_hi:[1,0]
	v_cvt_pk_bf16_f32 v216, v216, v217
	v_cvt_pk_bf16_f32 v217, v218, v219
	v_pk_mul_f32 v[208:209], v[208:209], v[238:239] op_sel_hi:[1,0]
	global_store_dwordx2 v[236:237], v[216:217], off offset:512
	v_pk_mul_f32 v[216:217], v[4:5], v[208:209]
	v_pk_mul_f32 v[218:219], v[6:7], v[210:211]
	v_pk_add_f32 v[208:209], v[54:55], 1.0 op_sel_hi:[1,0]
	v_pk_add_f32 v[210:211], v[52:53], 1.0 op_sel_hi:[1,0]
	v_pk_fma_f32 v[218:219], v[208:209], v[218:219], v[50:51]
	v_pk_fma_f32 v[216:217], v[210:211], v[216:217], v[48:49]
	v_pk_mul_f32 v[206:207], v[206:207], v[238:239] op_sel_hi:[1,0]
	v_cvt_pk_bf16_f32 v216, v216, v217
	v_cvt_pk_bf16_f32 v217, v218, v219
	v_pk_mul_f32 v[204:205], v[204:205], v[238:239] op_sel_hi:[1,0]
	global_store_dwordx2 v[236:237], v[216:217], off offset:1024
	v_pk_mul_f32 v[216:217], v[12:13], v[204:205]
	v_pk_mul_f32 v[218:219], v[14:15], v[206:207]
	v_pk_add_f32 v[204:205], v[78:79], 1.0 op_sel_hi:[1,0]
	v_pk_add_f32 v[206:207], v[76:77], 1.0 op_sel_hi:[1,0]
	v_pk_fma_f32 v[218:219], v[204:205], v[218:219], v[74:75]
	v_pk_fma_f32 v[216:217], v[206:207], v[216:217], v[72:73]
	v_cmp_lt_i32_e32 vcc, v194, v226
	v_cvt_pk_bf16_f32 v216, v216, v217
	v_cvt_pk_bf16_f32 v217, v218, v219
	global_store_dwordx2 v[236:237], v[216:217], off offset:1536
	s_and_saveexec_b64 s[6:7], vcc
	s_cbranch_execz .LBB0_1167
	s_waitcnt vmcnt(43)
	v_lshlrev_b32_e32 v216, 16, v202
	v_and_b32_e32 v217, 0xffff0000, v202
	v_lshlrev_b32_e32 v202, 16, v203
	v_and_b32_e32 v203, 0xffff0000, v203
	v_pk_add_f32 v[126:127], v[126:127], v[202:203]
	s_waitcnt vmcnt(42)
	v_lshlrev_b32_e32 v202, 16, v200
	v_and_b32_e32 v203, 0xffff0000, v200
	v_lshlrev_b32_e32 v200, 16, v201
	v_and_b32_e32 v201, 0xffff0000, v201
	v_pk_add_f32 v[122:123], v[122:123], v[200:201]
	s_waitcnt vmcnt(41)
	v_lshlrev_b32_e32 v200, 16, v198
	v_and_b32_e32 v201, 0xffff0000, v198
	v_lshlrev_b32_e32 v198, 16, v199
	v_and_b32_e32 v199, 0xffff0000, v199
	v_ashrrev_i32_e32 v195, 31, v194
	v_pk_add_f32 v[124:125], v[124:125], v[216:217]
	v_pk_add_f32 v[118:119], v[118:119], v[198:199]
	s_waitcnt vmcnt(40)
	v_lshlrev_b32_e32 v198, 16, v196
	v_and_b32_e32 v199, 0xffff0000, v196
	v_lshlrev_b32_e32 v196, 16, v197
	v_and_b32_e32 v197, 0xffff0000, v197
	v_add_u32_e32 v129, 0xffffe001, v128
	v_lshlrev_b64 v[194:195], 11, v[194:195]
	v_pk_add_f32 v[120:121], v[120:121], v[202:203]
	v_pk_add_f32 v[114:115], v[114:115], v[196:197]
	v_pk_add_f32 v[112:113], v[112:113], v[198:199]
	v_ashrrev_i32_e32 v129, 10, v129
	v_lshl_add_u64 v[196:197], v[134:135], 0, v[194:195]
	v_cvt_pk_bf16_f32 v198, v124, v125
	v_cvt_pk_bf16_f32 v199, v126, v127
	v_pk_add_f32 v[116:117], v[116:117], v[200:201]
	v_add_u32_e32 v129, 1, v129
	v_cmp_lt_i32_e32 vcc, s29, v128
	global_store_dwordx2 v[196:197], v[198:199], off
	v_cvt_pk_bf16_f32 v198, v120, v121
	v_cvt_pk_bf16_f32 v199, v122, v123
	v_cndmask_b32_e32 v129, 0, v129, vcc
	global_store_dwordx2 v[196:197], v[198:199], off offset:512
	v_cvt_pk_bf16_f32 v198, v116, v117
	v_cvt_pk_bf16_f32 v199, v118, v119
	global_store_dwordx2 v[196:197], v[198:199], off offset:1024
	v_cvt_pk_bf16_f32 v198, v112, v113
	v_cvt_pk_bf16_f32 v199, v114, v115
	v_cmp_ne_u32_e32 vcc, v129, v235
	global_store_dwordx2 v[196:197], v[198:199], off offset:1536
	s_and_saveexec_b64 s[40:41], vcc
	s_cbranch_execz .LBB0_1153
	global_load_dwordx4 v[16:19], v[136:137], off
	global_load_dwordx4 v[20:23], v[138:139], off
	v_mad_i64_i32 v[196:197], s[42:43], v129, s16, v[152:153]
	s_mov_b64 s[42:43], 0

.LBB0_1153:
	s_or_b64 exec, exec, s[40:41]
	v_mov_b32_e32 v198, v125
	v_mov_b32_e32 v199, v121
	v_mov_b32_e32 v196, v124
	v_mov_b32_e32 v197, v120
	v_pk_mul_f32 v[198:199], v[198:199], v[198:199]
	v_mov_b32_e32 v200, v117
	v_pk_fma_f32 v[196:197], v[196:197], v[196:197], v[198:199]
	v_mov_b32_e32 v198, v126
	v_mov_b32_e32 v199, v122
	v_pk_fma_f32 v[196:197], v[198:199], v[198:199], v[196:197]
	v_mov_b32_e32 v198, v127
	v_mov_b32_e32 v199, v123
	v_mov_b32_e32 v201, v113
	v_pk_fma_f32 v[196:197], v[198:199], v[198:199], v[196:197]
	v_mov_b32_e32 v198, v116
	v_mov_b32_e32 v199, v112
	v_pk_mul_f32 v[200:201], v[200:201], v[200:201]
	v_add_f32_e32 v129, v196, v197
	v_pk_fma_f32 v[198:199], v[198:199], v[198:199], v[200:201]
	v_mov_b32_e32 v200, v118
	v_mov_b32_e32 v201, v114
	v_pk_fma_f32 v[198:199], v[200:201], v[200:201], v[198:199]
	v_mov_b32_e32 v200, v119
	v_mov_b32_e32 v201, v115
	v_pk_fma_f32 v[198:199], v[200:201], v[200:201], v[198:199]
	v_lshl_add_u64 v[194:195], v[132:133], 0, v[194:195]
	v_add_f32_e32 v129, v129, v198
	v_add_f32_e32 v129, v129, v199
	ds_bpermute_b32 v155, v228, v129
	s_waitcnt lgkmcnt(0)
	v_add_f32_e32 v129, v129, v155
	ds_bpermute_b32 v155, v229, v129
	s_waitcnt lgkmcnt(0)
	v_add_f32_e32 v129, v129, v155
	s_nop 1
	v_add_f32_dpp v129, v129, v129 row_ror:8 row_mask:0xf bank_mask:0xf
	s_nop 1
	v_add_f32_dpp v129, v129, v129 row_ror:4 row_mask:0xf bank_mask:0xf
	s_nop 1
	v_add_f32_dpp v129, v129, v129 quad_perm:[2,3,0,1] row_mask:0xf bank_mask:0xf
	s_nop 1
	v_add_f32_dpp v129, v129, v129 quad_perm:[1,0,3,2] row_mask:0xf bank_mask:0xf
	v_fmamk_f32 v129, v129, 0x3a800000, v234
	v_mul_f32_e32 v155, 0x4b800000, v129
	v_cmp_gt_f32_e32 vcc, s28, v129
	s_nop 1
	v_cndmask_b32_e32 v129, v129, v155, vcc
	v_rsq_f32_e32 v129, v129
	s_nop 0
	v_mul_f32_e32 v155, 0x45800000, v129
	v_cndmask_b32_e32 v196, v129, v155, vcc
	v_pk_mul_f32 v[126:127], v[126:127], v[196:197] op_sel_hi:[1,0]
	v_pk_mul_f32 v[124:125], v[124:125], v[196:197] op_sel_hi:[1,0]
	v_pk_mul_f32 v[122:123], v[122:123], v[196:197] op_sel_hi:[1,0]
	v_pk_mul_f32 v[120:121], v[120:121], v[196:197] op_sel_hi:[1,0]
	v_pk_mul_f32 v[118:119], v[118:119], v[196:197] op_sel_hi:[1,0]
	v_pk_mul_f32 v[116:117], v[116:117], v[196:197] op_sel_hi:[1,0]
	v_pk_mul_f32 v[114:115], v[114:115], v[196:197] op_sel_hi:[1,0]
	v_pk_mul_f32 v[112:113], v[112:113], v[196:197] op_sel_hi:[1,0]
	v_pk_mul_f32 v[124:125], v[8:9], v[124:125]
	v_pk_mul_f32 v[126:127], v[10:11], v[126:127]
	v_pk_mul_f32 v[120:121], v[0:1], v[120:121]
	v_pk_mul_f32 v[122:123], v[2:3], v[122:123]
	v_pk_mul_f32 v[116:117], v[4:5], v[116:117]
	v_pk_mul_f32 v[118:119], v[6:7], v[118:119]
	v_pk_mul_f32 v[112:113], v[12:13], v[112:113]
	v_pk_mul_f32 v[114:115], v[14:15], v[114:115]
	v_pk_fma_f32 v[126:127], v[220:221], v[126:127], v[18:19]
	v_pk_fma_f32 v[124:125], v[222:223], v[124:125], v[16:17]
	v_pk_fma_f32 v[122:123], v[212:213], v[122:123], v[26:27]
	v_pk_fma_f32 v[120:121], v[214:215], v[120:121], v[24:25]
	v_pk_fma_f32 v[118:119], v[208:209], v[118:119], v[50:51]
	v_pk_fma_f32 v[116:117], v[210:211], v[116:117], v[48:49]
	v_pk_fma_f32 v[114:115], v[204:205], v[114:115], v[74:75]
	v_pk_fma_f32 v[112:113], v[206:207], v[112:113], v[72:73]
	v_cvt_pk_bf16_f32 v124, v124, v125
	v_cvt_pk_bf16_f32 v125, v126, v127
	v_cvt_pk_bf16_f32 v120, v120, v121
	v_cvt_pk_bf16_f32 v121, v122, v123
	v_cvt_pk_bf16_f32 v116, v116, v117
	v_cvt_pk_bf16_f32 v117, v118, v119
	v_cvt_pk_bf16_f32 v112, v112, v113
	v_cvt_pk_bf16_f32 v113, v114, v115
	global_store_dwordx2 v[194:195], v[124:125], off
	global_store_dwordx2 v[194:195], v[120:121], off offset:512
	global_store_dwordx2 v[194:195], v[116:117], off offset:1024
	global_store_dwordx2 v[194:195], v[112:113], off offset:1536
	s_or_b64 exec, exec, s[6:7]
	v_cmp_lt_i32_e32 vcc, v184, v226
	s_and_saveexec_b64 s[6:7], vcc
	s_cbranch_execnz .LBB0_1168

.LBB0_1165:
	s_or_b64 exec, exec, s[40:41]
	v_mov_b32_e32 v100, v93
	v_mov_b32_e32 v101, v89
	v_mov_b32_e32 v98, v92
	v_mov_b32_e32 v99, v88
	v_pk_mul_f32 v[100:101], v[100:101], v[100:101]
	v_mov_b32_e32 v102, v85
	v_pk_fma_f32 v[98:99], v[98:99], v[98:99], v[100:101]
	v_mov_b32_e32 v100, v94
	v_mov_b32_e32 v101, v90
	v_pk_fma_f32 v[98:99], v[100:101], v[100:101], v[98:99]
	v_mov_b32_e32 v100, v95
	v_mov_b32_e32 v101, v91
	v_mov_b32_e32 v103, v81
	v_pk_fma_f32 v[98:99], v[100:101], v[100:101], v[98:99]
	v_mov_b32_e32 v100, v84
	v_mov_b32_e32 v101, v80
	v_pk_mul_f32 v[102:103], v[102:103], v[102:103]
	v_add_f32_e32 v98, v98, v99
	v_pk_fma_f32 v[100:101], v[100:101], v[100:101], v[102:103]
	v_mov_b32_e32 v102, v86
	v_mov_b32_e32 v103, v82
	v_pk_fma_f32 v[100:101], v[102:103], v[102:103], v[100:101]
	v_mov_b32_e32 v102, v87
	v_mov_b32_e32 v103, v83
	v_pk_fma_f32 v[100:101], v[102:103], v[102:103], v[100:101]
	v_lshl_add_u64 v[96:97], v[132:133], 0, v[96:97]
	v_add_f32_e32 v98, v98, v100
	v_add_f32_e32 v98, v98, v101
	ds_bpermute_b32 v99, v228, v98
	v_pk_add_f32 v[100:101], v[20:21], 1.0 op_sel_hi:[1,0]
	s_waitcnt lgkmcnt(0)
	v_add_f32_e32 v98, v98, v99
	ds_bpermute_b32 v99, v229, v98
	s_waitcnt lgkmcnt(0)
	v_add_f32_e32 v98, v98, v99
	s_nop 1
	v_add_f32_dpp v98, v98, v98 row_ror:8 row_mask:0xf bank_mask:0xf
	s_nop 1
	v_add_f32_dpp v98, v98, v98 row_ror:4 row_mask:0xf bank_mask:0xf
	s_nop 1
	v_add_f32_dpp v98, v98, v98 quad_perm:[2,3,0,1] row_mask:0xf bank_mask:0xf
	s_nop 1
	v_add_f32_dpp v98, v98, v98 quad_perm:[1,0,3,2] row_mask:0xf bank_mask:0xf
	v_fmamk_f32 v98, v98, 0x3a800000, v234
	v_mul_f32_e32 v99, 0x4b800000, v98
	v_cmp_gt_f32_e32 vcc, s28, v98
	s_nop 1
	v_cndmask_b32_e32 v98, v98, v99, vcc
	v_rsq_f32_e32 v102, v98
	v_pk_add_f32 v[98:99], v[22:23], 1.0 op_sel_hi:[1,0]
	v_mul_f32_e32 v103, 0x45800000, v102
	v_cndmask_b32_e32 v102, v102, v103, vcc
	v_pk_mul_f32 v[94:95], v[94:95], v[102:103] op_sel_hi:[1,0]
	v_pk_mul_f32 v[92:93], v[92:93], v[102:103] op_sel_hi:[1,0]
	v_pk_mul_f32 v[94:95], v[10:11], v[94:95]
	v_pk_mul_f32 v[92:93], v[8:9], v[92:93]
	v_pk_fma_f32 v[94:95], v[98:99], v[94:95], v[18:19]
	v_pk_fma_f32 v[92:93], v[100:101], v[92:93], v[16:17]
	v_pk_mul_f32 v[90:91], v[90:91], v[102:103] op_sel_hi:[1,0]
	v_cvt_pk_bf16_f32 v92, v92, v93
	v_cvt_pk_bf16_f32 v93, v94, v95
	v_pk_mul_f32 v[88:89], v[88:89], v[102:103] op_sel_hi:[1,0]
	global_store_dwordx2 v[96:97], v[92:93], off
	v_pk_mul_f32 v[88:89], v[0:1], v[88:89]
	v_pk_mul_f32 v[90:91], v[2:3], v[90:91]
	v_pk_add_f32 v[92:93], v[30:31], 1.0 op_sel_hi:[1,0]
	v_pk_add_f32 v[94:95], v[28:29], 1.0 op_sel_hi:[1,0]
	v_pk_fma_f32 v[90:91], v[92:93], v[90:91], v[26:27]
	v_pk_fma_f32 v[88:89], v[94:95], v[88:89], v[24:25]
	v_pk_mul_f32 v[86:87], v[86:87], v[102:103] op_sel_hi:[1,0]
	v_cvt_pk_bf16_f32 v88, v88, v89
	v_cvt_pk_bf16_f32 v89, v90, v91
	v_pk_mul_f32 v[84:85], v[84:85], v[102:103] op_sel_hi:[1,0]
	global_store_dwordx2 v[96:97], v[88:89], off offset:512
	v_pk_mul_f32 v[84:85], v[4:5], v[84:85]
	v_pk_mul_f32 v[86:87], v[6:7], v[86:87]
	v_pk_add_f32 v[88:89], v[54:55], 1.0 op_sel_hi:[1,0]
	v_pk_add_f32 v[90:91], v[52:53], 1.0 op_sel_hi:[1,0]
	v_pk_fma_f32 v[86:87], v[88:89], v[86:87], v[50:51]
	v_pk_fma_f32 v[84:85], v[90:91], v[84:85], v[48:49]
	v_pk_mul_f32 v[82:83], v[82:83], v[102:103] op_sel_hi:[1,0]
	v_cvt_pk_bf16_f32 v84, v84, v85
	v_cvt_pk_bf16_f32 v85, v86, v87
	v_pk_mul_f32 v[80:81], v[80:81], v[102:103] op_sel_hi:[1,0]
	global_store_dwordx2 v[96:97], v[84:85], off offset:1024
	v_pk_mul_f32 v[80:81], v[12:13], v[80:81]
	v_pk_mul_f32 v[82:83], v[14:15], v[82:83]
	v_pk_add_f32 v[84:85], v[78:79], 1.0 op_sel_hi:[1,0]
	v_pk_add_f32 v[86:87], v[76:77], 1.0 op_sel_hi:[1,0]
	v_pk_fma_f32 v[82:83], v[84:85], v[82:83], v[74:75]
	v_pk_fma_f32 v[80:81], v[86:87], v[80:81], v[72:73]
	s_nop 0
	v_cvt_pk_bf16_f32 v80, v80, v81
	v_cvt_pk_bf16_f32 v81, v82, v83
	global_store_dwordx2 v[96:97], v[80:81], off offset:1536
	s_or_b64 exec, exec, s[6:7]
	v_cmp_lt_i32_e32 vcc, v164, v226
	s_and_saveexec_b64 s[6:7], vcc
	s_cbranch_execnz .LBB0_1180

.LBB0_1178:
	s_or_b64 exec, exec, s[40:41]
	v_mov_b32_e32 v116, v109
	v_mov_b32_e32 v117, v105
	v_mov_b32_e32 v114, v108
	v_mov_b32_e32 v115, v104
	v_pk_mul_f32 v[116:117], v[116:117], v[116:117]
	v_mov_b32_e32 v118, v101
	v_pk_fma_f32 v[114:115], v[114:115], v[114:115], v[116:117]
	v_mov_b32_e32 v116, v110
	v_mov_b32_e32 v117, v106
	v_pk_fma_f32 v[114:115], v[116:117], v[116:117], v[114:115]
	v_mov_b32_e32 v116, v111
	v_mov_b32_e32 v117, v107
	v_mov_b32_e32 v119, v97
	v_pk_fma_f32 v[114:115], v[116:117], v[116:117], v[114:115]
	v_mov_b32_e32 v116, v100
	v_mov_b32_e32 v117, v96
	v_pk_mul_f32 v[118:119], v[118:119], v[118:119]
	v_add_f32_e32 v114, v114, v115
	v_pk_fma_f32 v[116:117], v[116:117], v[116:117], v[118:119]
	v_mov_b32_e32 v118, v102
	v_mov_b32_e32 v119, v98
	v_pk_fma_f32 v[116:117], v[118:119], v[118:119], v[116:117]
	v_mov_b32_e32 v118, v103
	v_mov_b32_e32 v119, v99
	v_pk_fma_f32 v[116:117], v[118:119], v[118:119], v[116:117]
	v_lshl_add_u64 v[112:113], v[132:133], 0, v[112:113]
	v_add_f32_e32 v114, v114, v116
	v_add_f32_e32 v114, v114, v117
	ds_bpermute_b32 v115, v228, v114
	v_pk_add_f32 v[116:117], v[20:21], 1.0 op_sel_hi:[1,0]
	s_waitcnt lgkmcnt(0)
	v_add_f32_e32 v114, v114, v115
	ds_bpermute_b32 v115, v229, v114
	s_waitcnt lgkmcnt(0)
	v_add_f32_e32 v114, v114, v115
	s_nop 1
	v_add_f32_dpp v114, v114, v114 row_ror:8 row_mask:0xf bank_mask:0xf
	s_nop 1
	v_add_f32_dpp v114, v114, v114 row_ror:4 row_mask:0xf bank_mask:0xf
	s_nop 1
	v_add_f32_dpp v114, v114, v114 quad_perm:[2,3,0,1] row_mask:0xf bank_mask:0xf
	s_nop 1
	v_add_f32_dpp v114, v114, v114 quad_perm:[1,0,3,2] row_mask:0xf bank_mask:0xf
	v_fmamk_f32 v114, v114, 0x3a800000, v234
	v_mul_f32_e32 v115, 0x4b800000, v114
	v_cmp_gt_f32_e32 vcc, s28, v114
	s_nop 1
	v_cndmask_b32_e32 v114, v114, v115, vcc
	v_rsq_f32_e32 v118, v114
	v_pk_add_f32 v[114:115], v[22:23], 1.0 op_sel_hi:[1,0]
	v_mul_f32_e32 v119, 0x45800000, v118
	v_cndmask_b32_e32 v118, v118, v119, vcc
	v_pk_mul_f32 v[110:111], v[110:111], v[118:119] op_sel_hi:[1,0]
	v_pk_mul_f32 v[108:109], v[108:109], v[118:119] op_sel_hi:[1,0]
	v_pk_mul_f32 v[110:111], v[10:11], v[110:111]
	v_pk_mul_f32 v[108:109], v[8:9], v[108:109]
	v_pk_fma_f32 v[110:111], v[114:115], v[110:111], v[18:19]
	v_pk_fma_f32 v[108:109], v[116:117], v[108:109], v[16:17]
	v_pk_mul_f32 v[106:107], v[106:107], v[118:119] op_sel_hi:[1,0]
	v_cvt_pk_bf16_f32 v108, v108, v109
	v_cvt_pk_bf16_f32 v109, v110, v111
	v_pk_mul_f32 v[104:105], v[104:105], v[118:119] op_sel_hi:[1,0]
	global_store_dwordx2 v[112:113], v[108:109], off
	v_pk_mul_f32 v[104:105], v[0:1], v[104:105]
	v_pk_mul_f32 v[106:107], v[2:3], v[106:107]
	v_pk_add_f32 v[108:109], v[30:31], 1.0 op_sel_hi:[1,0]
	v_pk_add_f32 v[110:111], v[28:29], 1.0 op_sel_hi:[1,0]
	v_pk_fma_f32 v[106:107], v[108:109], v[106:107], v[26:27]
	v_pk_fma_f32 v[104:105], v[110:111], v[104:105], v[24:25]
	v_pk_mul_f32 v[102:103], v[102:103], v[118:119] op_sel_hi:[1,0]
	v_cvt_pk_bf16_f32 v104, v104, v105
	v_cvt_pk_bf16_f32 v105, v106, v107
	v_pk_mul_f32 v[100:101], v[100:101], v[118:119] op_sel_hi:[1,0]
	global_store_dwordx2 v[112:113], v[104:105], off offset:512
	v_pk_mul_f32 v[100:101], v[4:5], v[100:101]
	v_pk_mul_f32 v[102:103], v[6:7], v[102:103]
	v_pk_add_f32 v[104:105], v[54:55], 1.0 op_sel_hi:[1,0]
	v_pk_add_f32 v[106:107], v[52:53], 1.0 op_sel_hi:[1,0]
	v_pk_fma_f32 v[102:103], v[104:105], v[102:103], v[50:51]
	v_pk_fma_f32 v[100:101], v[106:107], v[100:101], v[48:49]
	v_pk_mul_f32 v[98:99], v[98:99], v[118:119] op_sel_hi:[1,0]
	v_cvt_pk_bf16_f32 v100, v100, v101
	v_cvt_pk_bf16_f32 v101, v102, v103
	v_pk_mul_f32 v[96:97], v[96:97], v[118:119] op_sel_hi:[1,0]
	global_store_dwordx2 v[112:113], v[100:101], off offset:1024
	v_pk_mul_f32 v[96:97], v[12:13], v[96:97]
	v_pk_mul_f32 v[98:99], v[14:15], v[98:99]
	v_pk_add_f32 v[100:101], v[78:79], 1.0 op_sel_hi:[1,0]
	v_pk_add_f32 v[102:103], v[76:77], 1.0 op_sel_hi:[1,0]
	v_pk_fma_f32 v[98:99], v[100:101], v[98:99], v[74:75]
	v_pk_fma_f32 v[96:97], v[102:103], v[96:97], v[72:73]
	s_nop 0
	v_cvt_pk_bf16_f32 v96, v96, v97
	v_cvt_pk_bf16_f32 v97, v98, v99
	global_store_dwordx2 v[112:113], v[96:97], off offset:1536
	s_or_b64 exec, exec, s[6:7]
	v_cmp_lt_i32_e32 vcc, v174, v226
	s_and_saveexec_b64 s[6:7], vcc
	s_cbranch_execnz .LBB0_1155

.LBB0_1190:
	s_or_b64 exec, exec, s[40:41]
	v_mov_b32_e32 v84, v69
	v_mov_b32_e32 v85, v65
	v_mov_b32_e32 v82, v68
	v_mov_b32_e32 v83, v64
	v_pk_mul_f32 v[84:85], v[84:85], v[84:85]
	v_mov_b32_e32 v86, v61
	v_pk_fma_f32 v[82:83], v[82:83], v[82:83], v[84:85]
	v_mov_b32_e32 v84, v70
	v_mov_b32_e32 v85, v66
	v_pk_fma_f32 v[82:83], v[84:85], v[84:85], v[82:83]
	v_mov_b32_e32 v84, v71
	v_mov_b32_e32 v85, v67
	v_mov_b32_e32 v87, v57
	v_pk_fma_f32 v[82:83], v[84:85], v[84:85], v[82:83]
	v_mov_b32_e32 v84, v60
	v_mov_b32_e32 v85, v56
	v_pk_mul_f32 v[86:87], v[86:87], v[86:87]
	v_add_f32_e32 v82, v82, v83
	v_pk_fma_f32 v[84:85], v[84:85], v[84:85], v[86:87]
	v_mov_b32_e32 v86, v62
	v_mov_b32_e32 v87, v58
	v_pk_fma_f32 v[84:85], v[86:87], v[86:87], v[84:85]
	v_mov_b32_e32 v86, v63
	v_mov_b32_e32 v87, v59
	v_pk_fma_f32 v[84:85], v[86:87], v[86:87], v[84:85]
	v_lshl_add_u64 v[80:81], v[132:133], 0, v[80:81]
	v_add_f32_e32 v82, v82, v84
	v_add_f32_e32 v82, v82, v85
	ds_bpermute_b32 v83, v228, v82
	v_pk_add_f32 v[84:85], v[20:21], 1.0 op_sel_hi:[1,0]
	s_waitcnt lgkmcnt(0)
	v_add_f32_e32 v82, v82, v83
	ds_bpermute_b32 v83, v229, v82
	s_waitcnt lgkmcnt(0)
	v_add_f32_e32 v82, v82, v83
	s_nop 1
	v_add_f32_dpp v82, v82, v82 row_ror:8 row_mask:0xf bank_mask:0xf
	s_nop 1
	v_add_f32_dpp v82, v82, v82 row_ror:4 row_mask:0xf bank_mask:0xf
	s_nop 1
	v_add_f32_dpp v82, v82, v82 quad_perm:[2,3,0,1] row_mask:0xf bank_mask:0xf
	s_nop 1
	v_add_f32_dpp v82, v82, v82 quad_perm:[1,0,3,2] row_mask:0xf bank_mask:0xf
	v_fmamk_f32 v82, v82, 0x3a800000, v234
	v_mul_f32_e32 v83, 0x4b800000, v82
	v_cmp_gt_f32_e32 vcc, s28, v82
	s_nop 1
	v_cndmask_b32_e32 v82, v82, v83, vcc
	v_rsq_f32_e32 v86, v82
	v_pk_add_f32 v[82:83], v[22:23], 1.0 op_sel_hi:[1,0]
	v_mul_f32_e32 v87, 0x45800000, v86
	v_cndmask_b32_e32 v86, v86, v87, vcc
	v_pk_mul_f32 v[70:71], v[70:71], v[86:87] op_sel_hi:[1,0]
	v_pk_mul_f32 v[68:69], v[68:69], v[86:87] op_sel_hi:[1,0]
	v_pk_mul_f32 v[70:71], v[10:11], v[70:71]
	v_pk_mul_f32 v[68:69], v[8:9], v[68:69]
	v_pk_fma_f32 v[70:71], v[82:83], v[70:71], v[18:19]
	v_pk_fma_f32 v[68:69], v[84:85], v[68:69], v[16:17]
	v_pk_mul_f32 v[66:67], v[66:67], v[86:87] op_sel_hi:[1,0]
	v_cvt_pk_bf16_f32 v68, v68, v69
	v_cvt_pk_bf16_f32 v69, v70, v71
	v_pk_mul_f32 v[64:65], v[64:65], v[86:87] op_sel_hi:[1,0]
	global_store_dwordx2 v[80:81], v[68:69], off
	v_pk_mul_f32 v[64:65], v[0:1], v[64:65]
	v_pk_mul_f32 v[66:67], v[2:3], v[66:67]
	v_pk_add_f32 v[68:69], v[30:31], 1.0 op_sel_hi:[1,0]
	v_pk_add_f32 v[70:71], v[28:29], 1.0 op_sel_hi:[1,0]
	v_pk_fma_f32 v[66:67], v[68:69], v[66:67], v[26:27]
	v_pk_fma_f32 v[64:65], v[70:71], v[64:65], v[24:25]
	v_pk_mul_f32 v[62:63], v[62:63], v[86:87] op_sel_hi:[1,0]
	v_cvt_pk_bf16_f32 v64, v64, v65
	v_cvt_pk_bf16_f32 v65, v66, v67
	v_pk_mul_f32 v[60:61], v[60:61], v[86:87] op_sel_hi:[1,0]
	global_store_dwordx2 v[80:81], v[64:65], off offset:512
	v_pk_mul_f32 v[60:61], v[4:5], v[60:61]
	v_pk_mul_f32 v[62:63], v[6:7], v[62:63]
	v_pk_add_f32 v[64:65], v[54:55], 1.0 op_sel_hi:[1,0]
	v_pk_add_f32 v[66:67], v[52:53], 1.0 op_sel_hi:[1,0]
	v_pk_fma_f32 v[62:63], v[64:65], v[62:63], v[50:51]
	v_pk_fma_f32 v[60:61], v[66:67], v[60:61], v[48:49]
	v_pk_mul_f32 v[58:59], v[58:59], v[86:87] op_sel_hi:[1,0]
	v_cvt_pk_bf16_f32 v60, v60, v61
	v_cvt_pk_bf16_f32 v61, v62, v63
	v_pk_mul_f32 v[56:57], v[56:57], v[86:87] op_sel_hi:[1,0]
	global_store_dwordx2 v[80:81], v[60:61], off offset:1024
	v_pk_mul_f32 v[56:57], v[12:13], v[56:57]
	v_pk_mul_f32 v[58:59], v[14:15], v[58:59]
	v_pk_add_f32 v[60:61], v[78:79], 1.0 op_sel_hi:[1,0]
	v_pk_add_f32 v[62:63], v[76:77], 1.0 op_sel_hi:[1,0]
	v_pk_fma_f32 v[58:59], v[60:61], v[58:59], v[74:75]
	v_pk_fma_f32 v[56:57], v[62:63], v[56:57], v[72:73]
	s_nop 0
	v_cvt_pk_bf16_f32 v56, v56, v57
	v_cvt_pk_bf16_f32 v57, v58, v59
	global_store_dwordx2 v[80:81], v[56:57], off offset:1536
	s_or_b64 exec, exec, s[6:7]
	v_cmp_lt_i32_e32 vcc, v154, v226
	s_and_saveexec_b64 s[6:7], vcc
	s_cbranch_execz .LBB0_1131

.LBB0_1559:
	v_add_u32_e32 v35, s90, v128
	s_waitcnt vmcnt(6)
	v_add_co_u32_e32 v36, vcc, s10, v24
	s_waitcnt vmcnt(4)
	v_min_i32_e32 v38, 0x2fff, v35
	v_addc_co_u32_e32 v37, vcc, -1, v25, vcc
	global_load_dwordx2 v[130:131], v[24:25], off
	global_load_dwordx2 v[132:133], v[36:37], off
	v_ashrrev_i32_e32 v39, 31, v38
	v_lshlrev_b64 v[38:39], 11, v[38:39]
	v_lshl_add_u64 v[40:41], v[16:17], 0, v[38:39]
	v_lshl_add_u64 v[38:39], v[18:19], 0, v[38:39]
	global_load_dwordx2 v[134:135], v[24:25], off offset:-512
	global_load_dwordx2 v[136:137], v[36:37], off offset:-512
	global_load_dwordx2 v[106:107], v[40:41], off
	global_load_dwordx2 v[110:111], v[40:41], off offset:512
	global_load_dwordx2 v[114:115], v[40:41], off offset:1024
	global_load_dwordx2 v[118:119], v[40:41], off offset:1536
	global_load_dwordx2 v[108:109], v[38:39], off
	global_load_dwordx2 v[112:113], v[38:39], off offset:512
	global_load_dwordx2 v[116:117], v[38:39], off offset:1024
	global_load_dwordx2 v[120:121], v[38:39], off offset:1536
	global_load_dwordx2 v[138:139], v[24:25], off offset:-1024
	global_load_dwordx2 v[140:141], v[36:37], off offset:-1024
	v_add_u32_e32 v88, s90, v129
	v_min_i32_e32 v38, 0x2fff, v88
	v_ashrrev_i32_e32 v39, 31, v38
	v_lshlrev_b64 v[38:39], 11, v[38:39]
	v_lshl_add_u64 v[40:41], v[16:17], 0, v[38:39]
	v_lshl_add_u64 v[38:39], v[18:19], 0, v[38:39]
	global_load_dwordx2 v[142:143], v[24:25], off offset:-1536
	global_load_dwordx2 v[102:103], v[40:41], off
	global_load_dwordx2 v[98:99], v[40:41], off offset:512
	global_load_dwordx2 v[94:95], v[40:41], off offset:1024
	global_load_dwordx2 v[90:91], v[40:41], off offset:1536
	global_load_dwordx2 v[144:145], v[36:37], off offset:-1536
	global_load_dwordx2 v[104:105], v[38:39], off
	global_load_dwordx2 v[100:101], v[38:39], off offset:512
	global_load_dwordx2 v[96:97], v[38:39], off offset:1024
	global_load_dwordx2 v[92:93], v[38:39], off offset:1536
	v_add_u32_e32 v70, s90, v30
	v_min_i32_e32 v36, 0x2fff, v70
	v_ashrrev_i32_e32 v37, 31, v36
	v_lshlrev_b64 v[36:37], 11, v[36:37]
	v_lshl_add_u64 v[38:39], v[16:17], 0, v[36:37]
	v_lshl_add_u64 v[36:37], v[18:19], 0, v[36:37]
	v_add_u32_e32 v52, s90, v29
	global_load_dwordx2 v[84:85], v[38:39], off
	global_load_dwordx2 v[80:81], v[38:39], off offset:512
	global_load_dwordx2 v[76:77], v[38:39], off offset:1024
	global_load_dwordx2 v[72:73], v[38:39], off offset:1536
	global_load_dwordx2 v[86:87], v[36:37], off
	global_load_dwordx2 v[82:83], v[36:37], off offset:512
	global_load_dwordx2 v[78:79], v[36:37], off offset:1024
	global_load_dwordx2 v[74:75], v[36:37], off offset:1536
	v_min_i32_e32 v36, 0x2fff, v52
	v_ashrrev_i32_e32 v37, 31, v36
	v_lshlrev_b64 v[36:37], 11, v[36:37]
	v_lshl_add_u64 v[38:39], v[16:17], 0, v[36:37]
	v_lshl_add_u64 v[36:37], v[18:19], 0, v[36:37]
	v_add_u32_e32 v34, s90, v28
	global_load_dwordx2 v[66:67], v[38:39], off
	global_load_dwordx2 v[62:63], v[38:39], off offset:512
	global_load_dwordx2 v[58:59], v[38:39], off offset:1024
	global_load_dwordx2 v[54:55], v[38:39], off offset:1536
	global_load_dwordx2 v[68:69], v[36:37], off
	global_load_dwordx2 v[64:65], v[36:37], off offset:512
	global_load_dwordx2 v[60:61], v[36:37], off offset:1024
	global_load_dwordx2 v[56:57], v[36:37], off offset:1536
	v_min_i32_e32 v36, 0x2fff, v34
	v_ashrrev_i32_e32 v37, 31, v36
	v_lshlrev_b64 v[36:37], 11, v[36:37]
	v_lshl_add_u64 v[38:39], v[16:17], 0, v[36:37]
	v_lshl_add_u64 v[146:147], v[18:19], 0, v[36:37]
	global_load_dwordx2 v[48:49], v[38:39], off
	global_load_dwordx2 v[44:45], v[38:39], off offset:512
	global_load_dwordx2 v[40:41], v[38:39], off offset:1024
	global_load_dwordx2 v[36:37], v[38:39], off offset:1536
	global_load_dwordx2 v[50:51], v[146:147], off
	global_load_dwordx2 v[46:47], v[146:147], off offset:512
	global_load_dwordx2 v[42:43], v[146:147], off offset:1024
	s_nop 0
	global_load_dwordx2 v[38:39], v[146:147], off offset:1536
	s_waitcnt vmcnt(47)
	v_lshlrev_b32_e32 v146, 16, v130
	v_and_b32_e32 v147, 0xffff0000, v130
	v_lshlrev_b32_e32 v130, 16, v131
	v_and_b32_e32 v131, 0xffff0000, v131
	s_waitcnt vmcnt(46)
	v_lshlrev_b32_e32 v148, 16, v132
	v_and_b32_e32 v149, 0xffff0000, v132
	v_lshlrev_b32_e32 v132, 16, v133
	v_and_b32_e32 v133, 0xffff0000, v133
	v_pk_add_f32 v[150:151], v[130:131], v[132:133]
	s_waitcnt vmcnt(45)
	v_lshlrev_b32_e32 v130, 16, v134
	v_and_b32_e32 v131, 0xffff0000, v134
	v_lshlrev_b32_e32 v132, 16, v135
	v_and_b32_e32 v133, 0xffff0000, v135
	s_waitcnt vmcnt(44)
	v_lshlrev_b32_e32 v134, 16, v136
	v_and_b32_e32 v135, 0xffff0000, v136
	v_lshlrev_b32_e32 v136, 16, v137
	v_and_b32_e32 v137, 0xffff0000, v137
	v_pk_add_f32 v[136:137], v[132:133], v[136:137]
	v_pk_add_f32 v[134:135], v[130:131], v[134:135]
	s_waitcnt vmcnt(35)
	v_lshlrev_b32_e32 v130, 16, v138
	v_and_b32_e32 v131, 0xffff0000, v138
	v_lshlrev_b32_e32 v132, 16, v139
	v_and_b32_e32 v133, 0xffff0000, v139
	s_waitcnt vmcnt(34)
	v_lshlrev_b32_e32 v138, 16, v140
	v_and_b32_e32 v139, 0xffff0000, v140
	v_lshlrev_b32_e32 v140, 16, v141
	v_and_b32_e32 v141, 0xffff0000, v141
	v_pk_add_f32 v[140:141], v[132:133], v[140:141]
	v_pk_add_f32 v[138:139], v[130:131], v[138:139]
	s_waitcnt vmcnt(33)
	v_lshlrev_b32_e32 v130, 16, v142
	v_and_b32_e32 v131, 0xffff0000, v142
	v_lshlrev_b32_e32 v132, 16, v143
	v_and_b32_e32 v133, 0xffff0000, v143
	s_waitcnt vmcnt(28)
	v_lshlrev_b32_e32 v142, 16, v144
	v_and_b32_e32 v143, 0xffff0000, v144
	v_lshlrev_b32_e32 v144, 16, v145
	v_and_b32_e32 v145, 0xffff0000, v145
	v_pk_add_f32 v[130:131], v[130:131], v[142:143]
	v_pk_add_f32 v[132:133], v[132:133], v[144:145]
	v_mov_b32_e32 v144, v139
	v_mov_b32_e32 v145, v131
	v_mov_b32_e32 v142, v138
	v_mov_b32_e32 v143, v130
	v_pk_mul_f32 v[144:145], v[144:145], v[144:145]
	v_pk_add_f32 v[146:147], v[146:147], v[148:149]
	v_pk_fma_f32 v[142:143], v[142:143], v[142:143], v[144:145]
	v_mov_b32_e32 v144, v140
	v_mov_b32_e32 v145, v132
	v_pk_fma_f32 v[142:143], v[144:145], v[144:145], v[142:143]
	v_mov_b32_e32 v144, v141
	v_mov_b32_e32 v145, v133
	v_mov_b32_e32 v148, v147
	v_mov_b32_e32 v149, v135
	v_pk_fma_f32 v[142:143], v[144:145], v[144:145], v[142:143]
	v_mov_b32_e32 v144, v146
	v_mov_b32_e32 v145, v134
	v_pk_mul_f32 v[148:149], v[148:149], v[148:149]
	v_add_f32_e32 v53, v142, v143
	v_pk_fma_f32 v[144:145], v[144:145], v[144:145], v[148:149]
	v_mov_b32_e32 v148, v150
	v_mov_b32_e32 v149, v136
	v_pk_fma_f32 v[144:145], v[148:149], v[148:149], v[144:145]
	v_mov_b32_e32 v148, v151
	v_mov_b32_e32 v149, v137
	v_pk_fma_f32 v[144:145], v[148:149], v[148:149], v[144:145]
	s_nop 0
	v_add_f32_e32 v53, v145, v53
	v_add_f32_e32 v53, v144, v53
	ds_bpermute_b32 v71, v122, v53
	v_lshl_add_u64 v[144:145], v[32:33], 0, v[22:23]
	s_waitcnt lgkmcnt(0)
	v_add_f32_e32 v53, v53, v71
	ds_bpermute_b32 v71, v123, v53
	s_waitcnt lgkmcnt(0)
	v_add_f32_e32 v53, v53, v71
	s_nop 1
	v_add_f32_dpp v53, v53, v53 row_ror:8 row_mask:0xf bank_mask:0xf
	s_nop 1
	v_add_f32_dpp v53, v53, v53 row_ror:4 row_mask:0xf bank_mask:0xf
	s_nop 1
	v_add_f32_dpp v53, v53, v53 quad_perm:[2,3,0,1] row_mask:0xf bank_mask:0xf
	s_nop 1
	v_add_f32_dpp v53, v53, v53 quad_perm:[1,0,3,2] row_mask:0xf bank_mask:0xf
	v_fmamk_f32 v53, v53, 0x3a800000, v31
	v_mul_f32_e32 v71, 0x4b800000, v53
	v_cmp_gt_f32_e32 vcc, s11, v53
	s_nop 1
	v_cndmask_b32_e32 v53, v53, v71, vcc
	v_rsq_f32_e32 v53, v53
	s_nop 0
	v_mul_f32_e32 v71, 0x45800000, v53
	v_cndmask_b32_e32 v142, v53, v71, vcc
	v_pk_mul_f32 v[130:131], v[130:131], v[142:143] op_sel_hi:[1,0]
	v_pk_mul_f32 v[132:133], v[132:133], v[142:143] op_sel_hi:[1,0]
	v_pk_mul_f32 v[130:131], v[0:1], v[130:131]
	v_pk_mul_f32 v[132:133], v[2:3], v[132:133]
	global_store_dwordx4 v[144:145], v[130:133], off nt
	v_cmp_gt_i32_e32 vcc, s8, v35
	s_nop 0
	v_pk_mul_f32 v[130:131], v[138:139], v[142:143] op_sel_hi:[1,0]
	v_pk_mul_f32 v[132:133], v[140:141], v[142:143] op_sel_hi:[1,0]
	v_pk_mul_f32 v[130:131], v[4:5], v[130:131]
	v_pk_mul_f32 v[132:133], v[6:7], v[132:133]
	global_store_dwordx4 v[144:145], v[130:133], off offset:1024 nt
	s_nop 1
	v_pk_mul_f32 v[130:131], v[134:135], v[142:143] op_sel_hi:[1,0]
	v_pk_mul_f32 v[132:133], v[136:137], v[142:143] op_sel_hi:[1,0]
	v_pk_mul_f32 v[130:131], v[8:9], v[130:131]
	v_pk_mul_f32 v[132:133], v[10:11], v[132:133]
	global_store_dwordx4 v[144:145], v[130:133], off offset:2048 nt
	s_nop 1
	v_pk_mul_f32 v[130:131], v[146:147], v[142:143] op_sel_hi:[1,0]
	v_pk_mul_f32 v[132:133], v[150:151], v[142:143] op_sel_hi:[1,0]
	v_pk_mul_f32 v[130:131], v[12:13], v[130:131]
	v_pk_mul_f32 v[132:133], v[14:15], v[132:133]
	global_store_dwordx4 v[144:145], v[130:133], off offset:3072 nt
	s_and_saveexec_b64 s[6:7], vcc
	s_cbranch_execz .LBB0_1561
	v_lshlrev_b32_e32 v130, 16, v118
	v_and_b32_e32 v131, 0xffff0000, v118
	v_lshlrev_b32_e32 v118, 16, v119
	v_and_b32_e32 v119, 0xffff0000, v119
	v_lshlrev_b32_e32 v132, 16, v120
	v_and_b32_e32 v133, 0xffff0000, v120
	v_lshlrev_b32_e32 v120, 16, v121
	v_and_b32_e32 v121, 0xffff0000, v121
	v_pk_add_f32 v[118:119], v[118:119], v[120:121]
	v_pk_add_f32 v[120:121], v[130:131], v[132:133]
	v_lshlrev_b32_e32 v130, 16, v114
	v_and_b32_e32 v131, 0xffff0000, v114
	v_lshlrev_b32_e32 v114, 16, v115
	v_and_b32_e32 v115, 0xffff0000, v115
	v_lshlrev_b32_e32 v132, 16, v116
	v_and_b32_e32 v133, 0xffff0000, v116
	v_lshlrev_b32_e32 v116, 16, v117
	v_and_b32_e32 v117, 0xffff0000, v117
	v_pk_add_f32 v[114:115], v[114:115], v[116:117]
	v_pk_add_f32 v[116:117], v[130:131], v[132:133]
	v_lshlrev_b32_e32 v130, 16, v110
	v_and_b32_e32 v131, 0xffff0000, v110
	v_lshlrev_b32_e32 v110, 16, v111
	v_and_b32_e32 v111, 0xffff0000, v111
	v_lshlrev_b32_e32 v132, 16, v112
	v_and_b32_e32 v133, 0xffff0000, v112
	v_lshlrev_b32_e32 v112, 16, v113
	v_and_b32_e32 v113, 0xffff0000, v113
	v_pk_add_f32 v[110:111], v[110:111], v[112:113]
	v_pk_add_f32 v[112:113], v[130:131], v[132:133]
	v_lshlrev_b32_e32 v130, 16, v106
	v_and_b32_e32 v131, 0xffff0000, v106
	v_lshlrev_b32_e32 v106, 16, v107
	v_and_b32_e32 v107, 0xffff0000, v107
	v_lshlrev_b32_e32 v132, 16, v108
	v_and_b32_e32 v133, 0xffff0000, v108
	v_lshlrev_b32_e32 v108, 16, v109
	v_and_b32_e32 v109, 0xffff0000, v109
	v_pk_add_f32 v[106:107], v[106:107], v[108:109]
	v_pk_add_f32 v[108:109], v[130:131], v[132:133]
	v_mov_b32_e32 v133, v113
	v_mov_b32_e32 v132, v109
	v_mov_b32_e32 v130, v108
	v_mov_b32_e32 v131, v112
	v_pk_mul_f32 v[132:133], v[132:133], v[132:133]
	v_mov_b32_e32 v134, v117
	v_pk_fma_f32 v[130:131], v[130:131], v[130:131], v[132:133]
	v_mov_b32_e32 v132, v106
	v_mov_b32_e32 v133, v110
	v_pk_fma_f32 v[130:131], v[132:133], v[132:133], v[130:131]
	v_mov_b32_e32 v132, v107
	v_mov_b32_e32 v133, v111
	v_mov_b32_e32 v135, v121
	v_pk_fma_f32 v[130:131], v[132:133], v[132:133], v[130:131]
	v_mov_b32_e32 v132, v116
	v_mov_b32_e32 v133, v120
	v_pk_mul_f32 v[134:135], v[134:135], v[134:135]
	v_add_f32_e32 v53, v130, v131
	v_pk_fma_f32 v[132:133], v[132:133], v[132:133], v[134:135]
	v_mov_b32_e32 v134, v114
	v_mov_b32_e32 v135, v118
	v_pk_fma_f32 v[132:133], v[134:135], v[134:135], v[132:133]
	v_mov_b32_e32 v134, v115
	v_mov_b32_e32 v135, v119
	v_pk_fma_f32 v[132:133], v[134:135], v[134:135], v[132:133]
	s_nop 0
	v_add_f32_e32 v53, v53, v132
	v_add_f32_e32 v53, v53, v133
	ds_bpermute_b32 v71, v122, v53
	v_lshl_add_u64 v[132:133], v[32:33], 0, v[26:27]
	s_waitcnt lgkmcnt(0)
	v_add_f32_e32 v53, v53, v71
	ds_bpermute_b32 v71, v123, v53
	s_waitcnt lgkmcnt(0)
	v_add_f32_e32 v53, v53, v71
	s_nop 1
	v_add_f32_dpp v53, v53, v53 row_ror:8 row_mask:0xf bank_mask:0xf
	s_nop 1
	v_add_f32_dpp v53, v53, v53 row_ror:4 row_mask:0xf bank_mask:0xf
	s_nop 1
	v_add_f32_dpp v53, v53, v53 quad_perm:[2,3,0,1] row_mask:0xf bank_mask:0xf
	s_nop 1
	v_add_f32_dpp v53, v53, v53 quad_perm:[1,0,3,2] row_mask:0xf bank_mask:0xf
	v_fmamk_f32 v53, v53, 0x3a800000, v31
	v_mul_f32_e32 v71, 0x4b800000, v53
	v_cmp_gt_f32_e32 vcc, s11, v53
	s_nop 1
	v_cndmask_b32_e32 v53, v53, v71, vcc
	v_rsq_f32_e32 v53, v53
	s_nop 0
	v_mul_f32_e32 v71, 0x45800000, v53
	v_cndmask_b32_e32 v130, v53, v71, vcc
	v_pk_mul_f32 v[134:135], v[108:109], v[130:131] op_sel_hi:[1,0]
	v_pk_mul_f32 v[106:107], v[106:107], v[130:131] op_sel_hi:[1,0]
	s_nop 0
	v_pk_mul_f32 v[108:109], v[2:3], v[106:107]
	v_pk_mul_f32 v[106:107], v[0:1], v[134:135]
	global_store_dwordx4 v[132:133], v[106:109], off nt
	s_nop 1
	v_pk_mul_f32 v[106:107], v[112:113], v[130:131] op_sel_hi:[1,0]
	v_pk_mul_f32 v[108:109], v[110:111], v[130:131] op_sel_hi:[1,0]
	v_pk_mul_f32 v[106:107], v[4:5], v[106:107]
	v_pk_mul_f32 v[108:109], v[6:7], v[108:109]
	global_store_dwordx4 v[132:133], v[106:109], off offset:1024 nt
	s_nop 1
	v_pk_mul_f32 v[106:107], v[116:117], v[130:131] op_sel_hi:[1,0]
	v_pk_mul_f32 v[108:109], v[114:115], v[130:131] op_sel_hi:[1,0]
	v_pk_mul_f32 v[106:107], v[8:9], v[106:107]
	v_pk_mul_f32 v[108:109], v[10:11], v[108:109]
	global_store_dwordx4 v[132:133], v[106:109], off offset:2048 nt
	s_nop 1
	v_pk_mul_f32 v[106:107], v[120:121], v[130:131] op_sel_hi:[1,0]
	v_pk_mul_f32 v[108:109], v[118:119], v[130:131] op_sel_hi:[1,0]
	v_pk_mul_f32 v[106:107], v[12:13], v[106:107]
	v_pk_mul_f32 v[108:109], v[14:15], v[108:109]
	global_store_dwordx4 v[132:133], v[106:109], off offset:3072 nt
.LBB0_1561:
	s_or_b64 exec, exec, s[6:7]
	v_add_u32_e32 v35, s33, v35
	v_cmp_gt_i32_e32 vcc, s8, v35
	s_and_saveexec_b64 s[6:7], vcc
	s_cbranch_execz .LBB0_1563
	s_waitcnt vmcnt(31)
	v_lshlrev_b32_e32 v106, 16, v104
	v_and_b32_e32 v107, 0xffff0000, v104
	v_lshlrev_b32_e32 v104, 16, v105
	v_and_b32_e32 v105, 0xffff0000, v105
	v_lshlrev_b32_e32 v108, 16, v102
	v_and_b32_e32 v109, 0xffff0000, v102
	v_lshlrev_b32_e32 v102, 16, v103
	v_and_b32_e32 v103, 0xffff0000, v103
	v_pk_add_f32 v[102:103], v[102:103], v[104:105]
	v_pk_add_f32 v[104:105], v[108:109], v[106:107]
	s_waitcnt vmcnt(30)
	v_lshlrev_b32_e32 v106, 16, v100
	v_and_b32_e32 v107, 0xffff0000, v100
	v_lshlrev_b32_e32 v100, 16, v101
	v_and_b32_e32 v101, 0xffff0000, v101
	v_lshlrev_b32_e32 v108, 16, v98
	v_and_b32_e32 v109, 0xffff0000, v98
	v_lshlrev_b32_e32 v98, 16, v99
	v_and_b32_e32 v99, 0xffff0000, v99
	v_pk_add_f32 v[98:99], v[98:99], v[100:101]
	v_pk_add_f32 v[100:101], v[108:109], v[106:107]
	s_waitcnt vmcnt(29)
	v_lshlrev_b32_e32 v106, 16, v96
	v_and_b32_e32 v107, 0xffff0000, v96
	v_lshlrev_b32_e32 v96, 16, v97
	v_and_b32_e32 v97, 0xffff0000, v97
	v_lshlrev_b32_e32 v108, 16, v94
	v_and_b32_e32 v109, 0xffff0000, v94
	v_lshlrev_b32_e32 v94, 16, v95
	v_and_b32_e32 v95, 0xffff0000, v95
	v_pk_add_f32 v[94:95], v[94:95], v[96:97]
	v_pk_add_f32 v[96:97], v[108:109], v[106:107]
	s_waitcnt vmcnt(28)
	v_lshlrev_b32_e32 v106, 16, v92
	v_and_b32_e32 v107, 0xffff0000, v92
	v_lshlrev_b32_e32 v108, 16, v90
	v_and_b32_e32 v109, 0xffff0000, v90
	v_lshlrev_b32_e32 v92, 16, v93
	v_and_b32_e32 v93, 0xffff0000, v93
	v_lshlrev_b32_e32 v90, 16, v91
	v_and_b32_e32 v91, 0xffff0000, v91
	v_pk_add_f32 v[106:107], v[108:109], v[106:107]
	v_mov_b32_e32 v108, v105
	v_mov_b32_e32 v109, v101
	v_pk_add_f32 v[92:93], v[90:91], v[92:93]
	v_mov_b32_e32 v90, v104
	v_mov_b32_e32 v91, v100
	v_pk_mul_f32 v[108:109], v[108:109], v[108:109]
	v_mov_b32_e32 v110, v97
	v_pk_fma_f32 v[90:91], v[90:91], v[90:91], v[108:109]
	v_mov_b32_e32 v108, v102
	v_mov_b32_e32 v109, v98
	v_pk_fma_f32 v[90:91], v[108:109], v[108:109], v[90:91]
	v_mov_b32_e32 v108, v103
	v_mov_b32_e32 v109, v99
	v_mov_b32_e32 v111, v107
	v_pk_fma_f32 v[90:91], v[108:109], v[108:109], v[90:91]
	v_mov_b32_e32 v108, v96
	v_mov_b32_e32 v109, v106
	v_pk_mul_f32 v[110:111], v[110:111], v[110:111]
	v_add_f32_e32 v53, v90, v91
	v_pk_fma_f32 v[108:109], v[108:109], v[108:109], v[110:111]
	v_mov_b32_e32 v110, v94
	v_mov_b32_e32 v111, v92
	v_pk_fma_f32 v[108:109], v[110:111], v[110:111], v[108:109]
	v_mov_b32_e32 v110, v95
	v_mov_b32_e32 v111, v93
	v_pk_fma_f32 v[108:109], v[110:111], v[110:111], v[108:109]
	v_ashrrev_i32_e32 v89, 31, v88
	v_add_f32_e32 v53, v53, v108
	v_add_f32_e32 v53, v53, v109
	ds_bpermute_b32 v71, v122, v53
	v_lshlrev_b64 v[88:89], 12, v[88:89]
	v_lshl_add_u64 v[110:111], v[20:21], 0, v[88:89]
	s_waitcnt lgkmcnt(0)
	v_add_f32_e32 v53, v53, v71
	ds_bpermute_b32 v71, v123, v53
	s_waitcnt lgkmcnt(0)
	v_add_f32_e32 v53, v53, v71
	s_nop 1
	v_add_f32_dpp v53, v53, v53 row_ror:8 row_mask:0xf bank_mask:0xf
	s_nop 1
	v_add_f32_dpp v53, v53, v53 row_ror:4 row_mask:0xf bank_mask:0xf
	s_nop 1
	v_add_f32_dpp v53, v53, v53 quad_perm:[2,3,0,1] row_mask:0xf bank_mask:0xf
	s_nop 1
	v_add_f32_dpp v53, v53, v53 quad_perm:[1,0,3,2] row_mask:0xf bank_mask:0xf
	v_fmamk_f32 v53, v53, 0x3a800000, v31
	v_mul_f32_e32 v71, 0x4b800000, v53
	v_cmp_gt_f32_e32 vcc, s11, v53
	s_nop 1
	v_cndmask_b32_e32 v53, v53, v71, vcc
	v_rsq_f32_e32 v53, v53
	s_nop 0
	v_mul_f32_e32 v71, 0x45800000, v53
	v_cndmask_b32_e32 v108, v53, v71, vcc
	v_pk_mul_f32 v[88:89], v[104:105], v[108:109] op_sel_hi:[1,0]
	v_pk_mul_f32 v[90:91], v[102:103], v[108:109] op_sel_hi:[1,0]
	v_pk_mul_f32 v[88:89], v[0:1], v[88:89]
	v_pk_mul_f32 v[90:91], v[2:3], v[90:91]
	global_store_dwordx4 v[110:111], v[88:91], off nt
	s_nop 1
	v_pk_mul_f32 v[88:89], v[100:101], v[108:109] op_sel_hi:[1,0]
	v_pk_mul_f32 v[90:91], v[98:99], v[108:109] op_sel_hi:[1,0]
	v_pk_mul_f32 v[88:89], v[4:5], v[88:89]
	v_pk_mul_f32 v[90:91], v[6:7], v[90:91]
	global_store_dwordx4 v[110:111], v[88:91], off offset:1024 nt
	s_nop 1
	v_pk_mul_f32 v[88:89], v[96:97], v[108:109] op_sel_hi:[1,0]
	v_pk_mul_f32 v[90:91], v[94:95], v[108:109] op_sel_hi:[1,0]
	v_pk_mul_f32 v[88:89], v[8:9], v[88:89]
	v_pk_mul_f32 v[90:91], v[10:11], v[90:91]
	global_store_dwordx4 v[110:111], v[88:91], off offset:2048 nt
	s_nop 1
	v_pk_mul_f32 v[88:89], v[106:107], v[108:109] op_sel_hi:[1,0]
	v_pk_mul_f32 v[90:91], v[92:93], v[108:109] op_sel_hi:[1,0]
	v_pk_mul_f32 v[88:89], v[12:13], v[88:89]
	v_pk_mul_f32 v[90:91], v[14:15], v[90:91]
	global_store_dwordx4 v[110:111], v[88:91], off offset:3072 nt
.LBB0_1563:
	s_or_b64 exec, exec, s[6:7]
	v_add_u32_e32 v35, s33, v35
	v_cmp_gt_i32_e32 vcc, s8, v35
	s_and_saveexec_b64 s[6:7], vcc
	s_cbranch_execz .LBB0_1565
	s_waitcnt vmcnt(23)
	v_lshlrev_b32_e32 v88, 16, v86
	v_and_b32_e32 v89, 0xffff0000, v86
	v_lshlrev_b32_e32 v86, 16, v87
	v_and_b32_e32 v87, 0xffff0000, v87
	v_lshlrev_b32_e32 v90, 16, v84
	v_and_b32_e32 v91, 0xffff0000, v84
	v_lshlrev_b32_e32 v84, 16, v85
	v_and_b32_e32 v85, 0xffff0000, v85
	v_pk_add_f32 v[84:85], v[84:85], v[86:87]
	v_pk_add_f32 v[86:87], v[90:91], v[88:89]
	s_waitcnt vmcnt(22)
	v_lshlrev_b32_e32 v88, 16, v82
	v_and_b32_e32 v89, 0xffff0000, v82
	v_lshlrev_b32_e32 v82, 16, v83
	v_and_b32_e32 v83, 0xffff0000, v83
	v_lshlrev_b32_e32 v90, 16, v80
	v_and_b32_e32 v91, 0xffff0000, v80
	v_lshlrev_b32_e32 v80, 16, v81
	v_and_b32_e32 v81, 0xffff0000, v81
	v_pk_add_f32 v[80:81], v[80:81], v[82:83]
	v_pk_add_f32 v[82:83], v[90:91], v[88:89]
	s_waitcnt vmcnt(21)
	v_lshlrev_b32_e32 v88, 16, v78
	v_and_b32_e32 v89, 0xffff0000, v78
	v_lshlrev_b32_e32 v78, 16, v79
	v_and_b32_e32 v79, 0xffff0000, v79
	v_lshlrev_b32_e32 v90, 16, v76
	v_and_b32_e32 v91, 0xffff0000, v76
	v_lshlrev_b32_e32 v76, 16, v77
	v_and_b32_e32 v77, 0xffff0000, v77
	v_pk_add_f32 v[76:77], v[76:77], v[78:79]
	v_pk_add_f32 v[78:79], v[90:91], v[88:89]
	s_waitcnt vmcnt(20)
	v_lshlrev_b32_e32 v88, 16, v74
	v_and_b32_e32 v89, 0xffff0000, v74
	v_lshlrev_b32_e32 v90, 16, v72
	v_and_b32_e32 v91, 0xffff0000, v72
	v_lshlrev_b32_e32 v74, 16, v75
	v_and_b32_e32 v75, 0xffff0000, v75
	v_lshlrev_b32_e32 v72, 16, v73
	v_and_b32_e32 v73, 0xffff0000, v73
	v_pk_add_f32 v[88:89], v[90:91], v[88:89]
	v_mov_b32_e32 v90, v87
	v_mov_b32_e32 v91, v83
	v_pk_add_f32 v[74:75], v[72:73], v[74:75]
	v_mov_b32_e32 v72, v86
	v_mov_b32_e32 v73, v82
	v_pk_mul_f32 v[90:91], v[90:91], v[90:91]
	v_mov_b32_e32 v92, v79
	v_pk_fma_f32 v[72:73], v[72:73], v[72:73], v[90:91]
	v_mov_b32_e32 v90, v84
	v_mov_b32_e32 v91, v80
	v_pk_fma_f32 v[72:73], v[90:91], v[90:91], v[72:73]
	v_mov_b32_e32 v90, v85
	v_mov_b32_e32 v91, v81
	v_mov_b32_e32 v93, v89
	v_pk_fma_f32 v[72:73], v[90:91], v[90:91], v[72:73]
	v_mov_b32_e32 v90, v78
	v_mov_b32_e32 v91, v88
	v_pk_mul_f32 v[92:93], v[92:93], v[92:93]
	v_add_f32_e32 v53, v72, v73
	v_pk_fma_f32 v[90:91], v[90:91], v[90:91], v[92:93]
	v_mov_b32_e32 v92, v76
	v_mov_b32_e32 v93, v74
	v_pk_fma_f32 v[90:91], v[92:93], v[92:93], v[90:91]
	v_mov_b32_e32 v92, v77
	v_mov_b32_e32 v93, v75
	v_pk_fma_f32 v[90:91], v[92:93], v[92:93], v[90:91]
	s_nop 0
	v_add_f32_e32 v53, v53, v90
	v_add_f32_e32 v53, v53, v91
	ds_bpermute_b32 v71, v122, v53
	s_waitcnt lgkmcnt(0)
	v_add_f32_e32 v53, v53, v71
	ds_bpermute_b32 v71, v123, v53
	s_waitcnt lgkmcnt(0)
	v_add_f32_e32 v53, v53, v71
	s_nop 1
	v_add_f32_dpp v53, v53, v53 row_ror:8 row_mask:0xf bank_mask:0xf
	s_nop 1
	v_add_f32_dpp v53, v53, v53 row_ror:4 row_mask:0xf bank_mask:0xf
	s_nop 1
	v_add_f32_dpp v53, v53, v53 quad_perm:[2,3,0,1] row_mask:0xf bank_mask:0xf
	s_nop 1
	v_add_f32_dpp v53, v53, v53 quad_perm:[1,0,3,2] row_mask:0xf bank_mask:0xf
	v_fmamk_f32 v53, v53, 0x3a800000, v31
	v_mul_f32_e32 v71, 0x4b800000, v53
	v_cmp_gt_f32_e32 vcc, s11, v53
	s_nop 1
	v_cndmask_b32_e32 v53, v53, v71, vcc
	v_rsq_f32_e32 v53, v53
	v_ashrrev_i32_e32 v71, 31, v70
	v_lshlrev_b64 v[70:71], 12, v[70:71]
	v_lshl_add_u64 v[92:93], v[20:21], 0, v[70:71]
	v_mul_f32_e32 v72, 0x45800000, v53
	v_cndmask_b32_e32 v90, v53, v72, vcc
	v_pk_mul_f32 v[70:71], v[86:87], v[90:91] op_sel_hi:[1,0]
	v_pk_mul_f32 v[72:73], v[84:85], v[90:91] op_sel_hi:[1,0]
	v_pk_mul_f32 v[70:71], v[0:1], v[70:71]
	v_pk_mul_f32 v[72:73], v[2:3], v[72:73]
	global_store_dwordx4 v[92:93], v[70:73], off nt
	s_nop 1
	v_pk_mul_f32 v[70:71], v[82:83], v[90:91] op_sel_hi:[1,0]
	v_pk_mul_f32 v[72:73], v[80:81], v[90:91] op_sel_hi:[1,0]
	v_pk_mul_f32 v[70:71], v[4:5], v[70:71]
	v_pk_mul_f32 v[72:73], v[6:7], v[72:73]
	global_store_dwordx4 v[92:93], v[70:73], off offset:1024 nt
	s_nop 1
	v_pk_mul_f32 v[70:71], v[78:79], v[90:91] op_sel_hi:[1,0]
	v_pk_mul_f32 v[72:73], v[76:77], v[90:91] op_sel_hi:[1,0]
	v_pk_mul_f32 v[70:71], v[8:9], v[70:71]
	v_pk_mul_f32 v[72:73], v[10:11], v[72:73]
	global_store_dwordx4 v[92:93], v[70:73], off offset:2048 nt
	s_nop 1
	v_pk_mul_f32 v[70:71], v[88:89], v[90:91] op_sel_hi:[1,0]
	v_pk_mul_f32 v[72:73], v[74:75], v[90:91] op_sel_hi:[1,0]
	v_pk_mul_f32 v[70:71], v[12:13], v[70:71]
	v_pk_mul_f32 v[72:73], v[14:15], v[72:73]
	global_store_dwordx4 v[92:93], v[70:73], off offset:3072 nt
.LBB0_1565:
	s_or_b64 exec, exec, s[6:7]
	v_add_u32_e32 v35, s33, v35
	v_cmp_gt_i32_e32 vcc, s8, v35
	s_and_saveexec_b64 s[6:7], vcc
	s_cbranch_execz .LBB0_1567
	s_waitcnt vmcnt(15)
	v_lshlrev_b32_e32 v70, 16, v68
	v_and_b32_e32 v71, 0xffff0000, v68
	v_lshlrev_b32_e32 v68, 16, v69
	v_and_b32_e32 v69, 0xffff0000, v69
	v_lshlrev_b32_e32 v72, 16, v66
	v_and_b32_e32 v73, 0xffff0000, v66
	v_lshlrev_b32_e32 v66, 16, v67
	v_and_b32_e32 v67, 0xffff0000, v67
	v_pk_add_f32 v[66:67], v[66:67], v[68:69]
	v_pk_add_f32 v[68:69], v[72:73], v[70:71]
	s_waitcnt vmcnt(14)
	v_lshlrev_b32_e32 v70, 16, v64
	v_and_b32_e32 v71, 0xffff0000, v64
	v_lshlrev_b32_e32 v64, 16, v65
	v_and_b32_e32 v65, 0xffff0000, v65
	v_lshlrev_b32_e32 v72, 16, v62
	v_and_b32_e32 v73, 0xffff0000, v62
	v_lshlrev_b32_e32 v62, 16, v63
	v_and_b32_e32 v63, 0xffff0000, v63
	v_pk_add_f32 v[62:63], v[62:63], v[64:65]
	v_pk_add_f32 v[64:65], v[72:73], v[70:71]
	s_waitcnt vmcnt(13)
	v_lshlrev_b32_e32 v70, 16, v60
	v_and_b32_e32 v71, 0xffff0000, v60
	v_lshlrev_b32_e32 v60, 16, v61
	v_and_b32_e32 v61, 0xffff0000, v61
	v_lshlrev_b32_e32 v72, 16, v58
	v_and_b32_e32 v73, 0xffff0000, v58
	v_lshlrev_b32_e32 v58, 16, v59
	v_and_b32_e32 v59, 0xffff0000, v59
	v_pk_add_f32 v[58:59], v[58:59], v[60:61]
	v_pk_add_f32 v[60:61], v[72:73], v[70:71]
	s_waitcnt vmcnt(12)
	v_lshlrev_b32_e32 v70, 16, v56
	v_and_b32_e32 v71, 0xffff0000, v56
	v_lshlrev_b32_e32 v72, 16, v54
	v_and_b32_e32 v73, 0xffff0000, v54
	v_lshlrev_b32_e32 v56, 16, v57
	v_and_b32_e32 v57, 0xffff0000, v57
	v_lshlrev_b32_e32 v54, 16, v55
	v_and_b32_e32 v55, 0xffff0000, v55
	v_pk_add_f32 v[70:71], v[72:73], v[70:71]
	v_mov_b32_e32 v72, v69
	v_mov_b32_e32 v73, v65
	v_pk_add_f32 v[56:57], v[54:55], v[56:57]
	v_mov_b32_e32 v54, v68
	v_mov_b32_e32 v55, v64
	v_pk_mul_f32 v[72:73], v[72:73], v[72:73]
	v_mov_b32_e32 v74, v61
	v_pk_fma_f32 v[54:55], v[54:55], v[54:55], v[72:73]
	v_mov_b32_e32 v72, v66
	v_mov_b32_e32 v73, v62
	v_pk_fma_f32 v[54:55], v[72:73], v[72:73], v[54:55]
	v_mov_b32_e32 v72, v67
	v_mov_b32_e32 v73, v63
	v_mov_b32_e32 v75, v71
	v_pk_fma_f32 v[54:55], v[72:73], v[72:73], v[54:55]
	v_mov_b32_e32 v72, v60
	v_mov_b32_e32 v73, v70
	v_pk_mul_f32 v[74:75], v[74:75], v[74:75]
	v_add_f32_e32 v53, v54, v55
	v_pk_fma_f32 v[72:73], v[72:73], v[72:73], v[74:75]
	v_mov_b32_e32 v74, v58
	v_mov_b32_e32 v75, v56
	v_pk_fma_f32 v[72:73], v[74:75], v[74:75], v[72:73]
	v_mov_b32_e32 v74, v59
	v_mov_b32_e32 v75, v57
	v_pk_fma_f32 v[72:73], v[74:75], v[74:75], v[72:73]
	s_nop 0
	v_add_f32_e32 v53, v53, v72
	v_add_f32_e32 v53, v53, v73
	ds_bpermute_b32 v54, v122, v53
	s_waitcnt lgkmcnt(0)
	v_add_f32_e32 v53, v53, v54
	ds_bpermute_b32 v54, v123, v53
	s_waitcnt lgkmcnt(0)
	v_add_f32_e32 v53, v53, v54
	s_nop 1
	v_add_f32_dpp v53, v53, v53 row_ror:8 row_mask:0xf bank_mask:0xf
	s_nop 1
	v_add_f32_dpp v53, v53, v53 row_ror:4 row_mask:0xf bank_mask:0xf
	s_nop 1
	v_add_f32_dpp v53, v53, v53 quad_perm:[2,3,0,1] row_mask:0xf bank_mask:0xf
	s_nop 1
	v_add_f32_dpp v53, v53, v53 quad_perm:[1,0,3,2] row_mask:0xf bank_mask:0xf
	v_fmamk_f32 v53, v53, 0x3a800000, v31
	v_mul_f32_e32 v54, 0x4b800000, v53
	v_cmp_gt_f32_e32 vcc, s11, v53
	s_nop 1
	v_cndmask_b32_e32 v53, v53, v54, vcc
	v_rsq_f32_e32 v54, v53
	v_ashrrev_i32_e32 v53, 31, v52
	v_lshlrev_b64 v[52:53], 12, v[52:53]
	v_lshl_add_u64 v[74:75], v[20:21], 0, v[52:53]
	v_mul_f32_e32 v55, 0x45800000, v54
	v_cndmask_b32_e32 v72, v54, v55, vcc
	v_pk_mul_f32 v[52:53], v[68:69], v[72:73] op_sel_hi:[1,0]
	v_pk_mul_f32 v[54:55], v[66:67], v[72:73] op_sel_hi:[1,0]
	v_pk_mul_f32 v[52:53], v[0:1], v[52:53]
	v_pk_mul_f32 v[54:55], v[2:3], v[54:55]
	global_store_dwordx4 v[74:75], v[52:55], off nt
	s_nop 1
	v_pk_mul_f32 v[52:53], v[64:65], v[72:73] op_sel_hi:[1,0]
	v_pk_mul_f32 v[54:55], v[62:63], v[72:73] op_sel_hi:[1,0]
	v_pk_mul_f32 v[52:53], v[4:5], v[52:53]
	v_pk_mul_f32 v[54:55], v[6:7], v[54:55]
	global_store_dwordx4 v[74:75], v[52:55], off offset:1024 nt
	s_nop 1
	v_pk_mul_f32 v[52:53], v[60:61], v[72:73] op_sel_hi:[1,0]
	v_pk_mul_f32 v[54:55], v[58:59], v[72:73] op_sel_hi:[1,0]
	v_pk_mul_f32 v[52:53], v[8:9], v[52:53]
	v_pk_mul_f32 v[54:55], v[10:11], v[54:55]
	global_store_dwordx4 v[74:75], v[52:55], off offset:2048 nt
	s_nop 1
	v_pk_mul_f32 v[52:53], v[70:71], v[72:73] op_sel_hi:[1,0]
	v_pk_mul_f32 v[54:55], v[56:57], v[72:73] op_sel_hi:[1,0]
	v_pk_mul_f32 v[52:53], v[12:13], v[52:53]
	v_pk_mul_f32 v[54:55], v[14:15], v[54:55]
	global_store_dwordx4 v[74:75], v[52:55], off offset:3072 nt
.LBB0_1567:
	s_or_b64 exec, exec, s[6:7]
	s_nop 0
	v_add_u32_e32 v52, s33, v35
	v_cmp_gt_i32_e32 vcc, s8, v52
	s_and_saveexec_b64 s[6:7], vcc
	s_cbranch_execz .LBB0_1558
	s_waitcnt vmcnt(7)
	v_lshlrev_b32_e32 v54, 16, v50
	v_and_b32_e32 v55, 0xffff0000, v50
	v_lshlrev_b32_e32 v50, 16, v51
	v_and_b32_e32 v51, 0xffff0000, v51
	v_lshlrev_b32_e32 v56, 16, v48
	v_and_b32_e32 v57, 0xffff0000, v48
	v_lshlrev_b32_e32 v48, 16, v49
	v_and_b32_e32 v49, 0xffff0000, v49
	v_pk_add_f32 v[48:49], v[48:49], v[50:51]
	v_pk_add_f32 v[50:51], v[56:57], v[54:55]
	s_waitcnt vmcnt(6)
	v_lshlrev_b32_e32 v54, 16, v46
	v_and_b32_e32 v55, 0xffff0000, v46
	v_lshlrev_b32_e32 v46, 16, v47
	v_and_b32_e32 v47, 0xffff0000, v47
	v_lshlrev_b32_e32 v56, 16, v44
	v_and_b32_e32 v57, 0xffff0000, v44
	v_lshlrev_b32_e32 v44, 16, v45
	v_and_b32_e32 v45, 0xffff0000, v45
	v_pk_add_f32 v[44:45], v[44:45], v[46:47]
	v_pk_add_f32 v[46:47], v[56:57], v[54:55]
	s_waitcnt vmcnt(5)
	v_lshlrev_b32_e32 v54, 16, v42
	v_and_b32_e32 v55, 0xffff0000, v42
	v_lshlrev_b32_e32 v42, 16, v43
	v_and_b32_e32 v43, 0xffff0000, v43
	v_lshlrev_b32_e32 v56, 16, v40
	v_and_b32_e32 v57, 0xffff0000, v40
	v_lshlrev_b32_e32 v40, 16, v41
	v_and_b32_e32 v41, 0xffff0000, v41
	v_pk_add_f32 v[40:41], v[40:41], v[42:43]
	v_pk_add_f32 v[42:43], v[56:57], v[54:55]
	s_waitcnt vmcnt(4)
	v_lshlrev_b32_e32 v54, 16, v38
	v_and_b32_e32 v55, 0xffff0000, v38
	v_lshlrev_b32_e32 v56, 16, v36
	v_and_b32_e32 v57, 0xffff0000, v36
	v_lshlrev_b32_e32 v38, 16, v39
	v_and_b32_e32 v39, 0xffff0000, v39
	v_lshlrev_b32_e32 v36, 16, v37
	v_and_b32_e32 v37, 0xffff0000, v37
	v_pk_add_f32 v[54:55], v[56:57], v[54:55]
	v_mov_b32_e32 v56, v51
	v_mov_b32_e32 v57, v47
	v_pk_add_f32 v[38:39], v[36:37], v[38:39]
	v_mov_b32_e32 v36, v50
	v_mov_b32_e32 v37, v46
	v_pk_mul_f32 v[56:57], v[56:57], v[56:57]
	v_mov_b32_e32 v58, v43
	v_pk_fma_f32 v[36:37], v[36:37], v[36:37], v[56:57]
	v_mov_b32_e32 v56, v48
	v_mov_b32_e32 v57, v44
	v_pk_fma_f32 v[36:37], v[56:57], v[56:57], v[36:37]
	v_mov_b32_e32 v56, v49
	v_mov_b32_e32 v57, v45
	v_mov_b32_e32 v59, v55
	v_pk_fma_f32 v[36:37], v[56:57], v[56:57], v[36:37]
	v_mov_b32_e32 v56, v42
	v_mov_b32_e32 v57, v54
	v_pk_mul_f32 v[58:59], v[58:59], v[58:59]
	v_add_f32_e32 v35, v36, v37
	v_pk_fma_f32 v[56:57], v[56:57], v[56:57], v[58:59]
	v_mov_b32_e32 v58, v40
	v_mov_b32_e32 v59, v38
	v_pk_fma_f32 v[56:57], v[58:59], v[58:59], v[56:57]
	v_mov_b32_e32 v58, v41
	v_mov_b32_e32 v59, v39
	v_pk_fma_f32 v[56:57], v[58:59], v[58:59], v[56:57]
	s_nop 0
	v_add_f32_e32 v35, v35, v56
	v_add_f32_e32 v35, v35, v57
	ds_bpermute_b32 v36, v122, v35
	s_waitcnt lgkmcnt(0)
	v_add_f32_e32 v35, v35, v36
	ds_bpermute_b32 v36, v123, v35
	s_waitcnt lgkmcnt(0)
	v_add_f32_e32 v35, v35, v36
	s_nop 1
	v_add_f32_dpp v35, v35, v35 row_ror:8 row_mask:0xf bank_mask:0xf
	s_nop 1
	v_add_f32_dpp v35, v35, v35 row_ror:4 row_mask:0xf bank_mask:0xf
	s_nop 1
	v_add_f32_dpp v35, v35, v35 quad_perm:[2,3,0,1] row_mask:0xf bank_mask:0xf
	s_nop 1
	v_add_f32_dpp v35, v35, v35 quad_perm:[1,0,3,2] row_mask:0xf bank_mask:0xf
	v_fmamk_f32 v35, v35, 0x3a800000, v31
	v_mul_f32_e32 v36, 0x4b800000, v35
	v_cmp_gt_f32_e32 vcc, s11, v35
	s_nop 1
	v_cndmask_b32_e32 v35, v35, v36, vcc
	v_rsq_f32_e32 v36, v35
	v_ashrrev_i32_e32 v35, 31, v34
	v_lshlrev_b64 v[34:35], 12, v[34:35]
	v_lshl_add_u64 v[58:59], v[20:21], 0, v[34:35]
	v_mul_f32_e32 v37, 0x45800000, v36
	v_cndmask_b32_e32 v56, v36, v37, vcc
	v_pk_mul_f32 v[34:35], v[50:51], v[56:57] op_sel_hi:[1,0]
	v_pk_mul_f32 v[36:37], v[48:49], v[56:57] op_sel_hi:[1,0]
	v_pk_mul_f32 v[34:35], v[0:1], v[34:35]
	v_pk_mul_f32 v[36:37], v[2:3], v[36:37]
	global_store_dwordx4 v[58:59], v[34:37], off nt
	s_nop 1
	v_pk_mul_f32 v[34:35], v[46:47], v[56:57] op_sel_hi:[1,0]
	v_pk_mul_f32 v[36:37], v[44:45], v[56:57] op_sel_hi:[1,0]
	v_pk_mul_f32 v[34:35], v[4:5], v[34:35]
	v_pk_mul_f32 v[36:37], v[6:7], v[36:37]
	global_store_dwordx4 v[58:59], v[34:37], off offset:1024 nt
	s_nop 1
	v_pk_mul_f32 v[34:35], v[42:43], v[56:57] op_sel_hi:[1,0]
	v_pk_mul_f32 v[36:37], v[40:41], v[56:57] op_sel_hi:[1,0]
	v_pk_mul_f32 v[34:35], v[8:9], v[34:35]
	v_pk_mul_f32 v[36:37], v[10:11], v[36:37]
	global_store_dwordx4 v[58:59], v[34:37], off offset:2048 nt
	s_nop 1
	v_pk_mul_f32 v[34:35], v[54:55], v[56:57] op_sel_hi:[1,0]
	v_pk_mul_f32 v[36:37], v[38:39], v[56:57] op_sel_hi:[1,0]
	v_pk_mul_f32 v[34:35], v[12:13], v[34:35]
	v_pk_mul_f32 v[36:37], v[14:15], v[36:37]
	global_store_dwordx4 v[58:59], v[34:37], off offset:3072 nt
	s_branch .LBB0_1558
